# v24 + LRU item loops no longer wait at the loop top for the previous item's global stores to be acknowledged
# speedup vs baseline: 1.0028x; 1.0028x over previous
; __device__ __forceinline__ int ltid(int wave) { int t = (wave << 6) | (int)__builtin_amdgcn_mbcnt_hi(~0u, __builtin_amdgcn_mbcnt_lo(~0u, 0u)); asm volatile("" : "+v"(t)); return t; }
; template <int PASS>
; __device__ void lru_items(const Params& p, unsigned char* shm, int l) {
;     ...
;     const bf16_t* XL = (const bf16_t*)(p.ws + B_XL); bf16_t* GL = (bf16_t*)(p.ws + B_GL); const bf16_t* LWT = (const bf16_t*)(p.ws + SM_LWT);
;     float* SA = (float*)(p.ws + SM_SA); float* SH = (float*)(p.ws + SM_SH); const float* CIN = (const float*)(p.ws + SM_CIN);
;     const float* cw = p.in[4] + l * 4096; const float* cbias = p.in[5] + l * 1024;
;     const int tid = ltid(p.wave), lane = tid & 63, w = tid >> 6, fr = lane & 15, fq = lane >> 4, G_ = gridDim.x, total = NCHK * 16;
;     int n_loaded = -1;
;     float c0 = 0.f, c1 = 0.f, c2 = 0.f, c3 = 0.f, cb = 0.f, gba[4], gbx[4], gsp[4];
; #pragma unroll
;     for (int jt = 0; jt < 4; ++jt) { gba[jt] = 0.f; gbx[jt] = 0.f; gsp[jt] = 0.f; }
;     u32x4 xr0 = (u32x4){0u, 0u, 0u, 0u}, xr1 = (u32x4){0u, 0u, 0u, 0u};
;     ...
;     int it = lbid();
;     if (it < total) LRU_LOAD(it);
;     for (; it < total; it += G_) {
;         const int ck = it >> 4, n = it & 15, t0 = ck * 64;
;         *(u32x4*)(xraw + (tid >> 3) * 64 + (tid & 7) * 8) = xr0;
;         if (tid < 24) *(u32x4*)(xraw + (64 + (tid >> 3)) * 64 + (tid & 7) * 8) = xr1;
;         if (n != n_loaded) {
;             n_loaded = n;
; #pragma unroll
;             for (int i = 0; i < 4; ++i) { const int e = tid + 512 * i, mtx = e >> 9, rem = e & 511, j = rem >> 3, c8 = rem & 7;
;                 *(u32x4*)(wt + (mtx * 64 + j) * 72 + c8 * 8) = *(const u32x4*)(LWT + ((size_t)(mtx * 16 + n) * 64 + j) * 64 + c8 * 8); }
;             { const int ch = n * 64 + (tid & 63); c0 = cw[ch]; c1 = cw[1024 + ch]; c2 = cw[2048 + ch]; c3 = cw[3072 + ch]; cb = cbias[ch]; }
; #pragma unroll
;             for (int jt = 0; jt < 4; ++jt) { const int pi = (l * 2 + (w >> 2)) * 1024 + n * 64 + jt * 16 + fr; gba[jt] = p.in[7][pi]; gbx[jt] = p.in[9][pi]; gsp[jt] = -8.0f * log1pf(__expf(-p.in[10][pi])); }
;         }
;         u32x4 glv = (u32x4){0u, 0u, 0u, 0u}; float cin = 0.f;
;         const size_t go = (size_t)(t0 + (tid >> 3)) * 1024 + n * 64 + (tid & 7) * 8;
;         const size_t so = (size_t)(ck * 2 + ((tid >> 6) & 1)) * 1024 + n * 64 + (tid & 63);
.LBB0_198:
	s_or_b64 exec, exec, s[0:1]
	v_readlane_b32 s0, v254, 43
	v_readlane_b32 s1, v254, 44
	s_mov_b32 s6, s0
	s_lshl_b32 s0, s0, 12
	s_ashr_i32 s1, s0, 31
	s_lshl_b32 s4, s6, 10
	v_readlane_b32 s60, v251, 20
	s_ashr_i32 s5, s4, 31
	s_lshl_b64 s[0:1], s[0:1], 2
	v_readlane_b32 s68, v251, 28
	v_readlane_b32 s61, v251, 21
	v_readlane_b32 s69, v251, 29
	s_add_u32 s60, s68, s0
	v_readlane_b32 s62, v251, 22
	v_readlane_b32 s70, v251, 30
	s_addc_u32 s61, s69, s1
	s_lshl_b64 s[0:1], s[4:5], 2
	v_readlane_b32 s63, v251, 23
	v_readlane_b32 s71, v251, 31
	s_add_u32 s62, s70, s0
	s_addc_u32 s63, s71, s1
	v_lshlrev_b32_e32 v0, 3, v142
	v_bfe_u32 v17, v142, 3, 6
	v_readlane_b32 s0, v252, 11
	v_and_b32_e32 v26, 56, v0
	v_lshlrev_b32_e32 v0, 7, v17
	v_readlane_b32 s1, v252, 12
	v_lshlrev_b32_e32 v10, 1, v26
	v_mov_b32_e32 v11, v1
	v_lshl_add_u64 v[12:13], s[0:1], 0, v[0:1]
	v_add_u32_e32 v16, 0, v10
	v_lshl_add_u64 v[28:29], v[12:13], 0, v[10:11]
	v_lshlrev_b32_e32 v10, 2, v142
	v_and_b32_e32 v0, 0xfffffc00, v10
	v_and_b32_e32 v43, 63, v142
	v_and_b32_e32 v14, 15, v142
	v_lshl_add_u32 v0, s6, 11, v0
	v_readlane_b32 s0, v252, 15
	v_lshlrev_b32_e32 v25, 8, v27
	v_lshlrev_b32_e32 v32, 2, v26
	v_readlane_b32 s4, v254, 6
	v_add_u32_e32 v33, 0x200, v142
	v_add_u32_e32 v34, 0x400, v142
	v_add_u32_e32 v35, 0x600, v142
	v_or_b32_e32 v45, v0, v14
	v_lshlrev_b32_e32 v0, 2, v43
	v_readlane_b32 s1, v252, 16
	v_add3_u32 v50, s4, v25, v32
	v_ashrrev_i32_e32 v32, 9, v142
	v_ashrrev_i32_e32 v33, 9, v33
	v_ashrrev_i32_e32 v34, 9, v34
	v_ashrrev_i32_e32 v35, 9, v35
	v_lshl_add_u64 v[30:31], s[0:1], 0, v[0:1]
	v_lshlrev_b32_e32 v0, 1, v43
	v_lshlrev_b32_e32 v52, 4, v32
	v_lshl_or_b32 v32, v32, 6, v17
	v_lshlrev_b32_e32 v53, 4, v33
	v_lshl_or_b32 v33, v33, 6, v17
	v_lshlrev_b32_e32 v54, 4, v34
	v_lshl_or_b32 v34, v34, 6, v17
	v_lshlrev_b32_e32 v55, 4, v35
	v_lshl_or_b32 v17, v35, 6, v17
	v_lshlrev_b32_e32 v35, 1, v142
	v_ashrrev_i32_e32 v15, 6, v142
	v_add_u32_e32 v11, 0, v0
	s_movk_i32 s0, 0x90
	v_and_b32_e32 v35, 0xffffff80, v35
	s_movk_i32 s6, 0x104
	v_and_b32_e32 v46, 1, v15
	v_lshlrev_b32_e32 v18, 4, v15
	v_add_u32_e32 v56, v11, v35
	v_add3_u32 v57, 0, v35, v0
	v_mul_lo_u32 v35, v15, s6
	v_mul_lo_u32 v36, v15, s0
	v_lshlrev_b32_e32 v15, 7, v15
	v_add_u32_e32 v37, 0x400, v15
	v_add_u32_e32 v58, v11, v37
	v_add3_u32 v59, 0, v37, v0
	v_add_u32_e32 v37, 0x800, v15
	v_add_u32_e32 v60, v11, v37
	v_add3_u32 v61, 0, v37, v0
	v_add_u32_e32 v37, 0xc00, v15
	v_and_b32_e32 v18, 48, v18
	v_and_b32_e32 v20, 48, v142
	v_add_u32_e32 v62, v11, v37
	v_add3_u32 v63, 0, v37, v0
	v_add_u32_e32 v37, 0x1000, v15
	v_ashrrev_i32_e32 v13, 8, v142
	v_or_b32_e32 v19, v18, v14
	v_add_u32_e32 v21, 0, v20
	v_add_u32_e32 v64, v11, v37
	v_add3_u32 v65, 0, v37, v0
	v_add_u32_e32 v37, 0x1400, v15
	v_mad_u32_u24 v47, v19, s0, v21
	v_lshl_or_b32 v19, v13, 7, v14
	v_lshrrev_b32_e32 v22, 2, v142
	v_add_u32_e32 v66, v11, v37
	v_add3_u32 v67, 0, v37, v0
	v_add_u32_e32 v37, 0x1800, v15
	v_add_u32_e32 v15, 0x1c00, v15
	v_add_u32_e32 v12, v11, v0
	v_and_or_b32 v18, v22, 12, v18
	v_lshlrev_b32_e32 v13, 12, v13
	v_add3_u32 v69, 0, v37, v0
	v_add3_u32 v71, 0, v15, v0
	v_mul_lo_u32 v0, v19, s0
	v_add_u32_e32 v72, v21, v0
	v_add3_u32 v73, 0, v0, v20
	v_lshl_or_b32 v0, v18, 6, v13
	v_or_b32_e32 v13, v0, v14
	v_readlane_b32 s5, v254, 7
	v_lshlrev_b32_e32 v13, 2, v13
	v_add_u32_e32 v75, s4, v13
	v_add_u32_e32 v74, s5, v13
	v_or_b32_e32 v13, 64, v0
	v_or_b32_e32 v19, v13, v14
	v_lshlrev_b32_e32 v19, 2, v19
	v_add_u32_e32 v76, s5, v19
	v_add_u32_e32 v77, s4, v19
	v_or_b32_e32 v19, 0x80, v0
	v_or_b32_e32 v20, v19, v14
	v_lshlrev_b32_e32 v20, 2, v20
	v_add_u32_e32 v78, s5, v20
	v_add_u32_e32 v79, s4, v20
	v_or_b32_e32 v20, 0xc0, v0
	v_or_b32_e32 v21, v20, v14
	v_lshlrev_b32_e32 v21, 2, v21
	v_add_u32_e32 v80, s5, v21
	v_add_u32_e32 v81, s4, v21
	v_or_b32_e32 v21, 16, v14
	v_add_u32_e32 v68, v11, v37
	v_or_b32_e32 v37, v0, v21
	v_lshlrev_b32_e32 v37, 2, v37
	v_add_u32_e32 v82, s5, v37
	v_add_u32_e32 v83, s4, v37
	v_or_b32_e32 v37, v13, v21
	v_lshlrev_b32_e32 v37, 2, v37
	v_add_u32_e32 v84, s5, v37
	v_add_u32_e32 v85, s4, v37
	v_or_b32_e32 v37, v19, v21
	v_or_b32_e32 v21, v20, v21
	v_lshlrev_b32_e32 v21, 2, v21
	v_add_u32_e32 v70, v11, v15
	v_lshl_add_u32 v15, v14, 2, 0
	v_lshlrev_b32_e32 v37, 2, v37
	v_add_u32_e32 v88, s5, v21
	v_add_u32_e32 v89, s4, v21
	v_or_b32_e32 v21, 32, v14
	v_or_b32_e32 v14, 48, v14
	v_add_u32_e32 v86, s5, v37
	v_add_u32_e32 v87, s4, v37
	v_or_b32_e32 v37, v0, v21
	v_or_b32_e32 v0, v0, v14
	v_lshlrev_b32_e32 v0, 2, v0
	v_add_u32_e32 v98, s5, v0
	v_add_u32_e32 v99, s4, v0
	v_or_b32_e32 v0, v13, v14
	v_lshlrev_b32_e32 v0, 2, v0
	v_add_u32_e32 v100, s5, v0
	v_add_u32_e32 v101, s4, v0
	v_or_b32_e32 v0, v19, v14
	v_lshlrev_b32_e32 v0, 2, v0
	v_ashrrev_i32_e32 v22, 7, v142
	v_add_u32_e32 v102, s5, v0
	v_add_u32_e32 v103, s4, v0
	v_or_b32_e32 v0, v20, v14
	v_lshlrev_b32_e32 v23, 4, v22
	v_lshlrev_b32_e32 v0, 2, v0
	v_lshlrev_b32_e32 v37, 2, v37
	v_add_u32_e32 v104, s5, v0
	v_add_u32_e32 v105, s4, v0
	v_or_b32_e32 v0, 1, v23
	v_cmp_eq_u32_e32 vcc, 0, v46
	v_add_u32_e32 v90, s5, v37
	v_add_u32_e32 v91, s4, v37
	v_or_b32_e32 v37, v13, v21
	v_sub_u32_e32 v13, 63, v0
; __device__ __forceinline__ int lbid() { int b = blockIdx.x; asm volatile("" : "+s"(b)); return b; }
; template <int PASS>
; __device__ void lru_items(const Params& p, unsigned char* shm, int l) {
;     ...
;     int n_loaded = -1;
;     float c0 = 0.f, c1 = 0.f, c2 = 0.f, c3 = 0.f, cb = 0.f, gba[4], gbx[4], gsp[4];
; #pragma unroll
;     for (int jt = 0; jt < 4; ++jt) { gba[jt] = 0.f; gbx[jt] = 0.f; gsp[jt] = 0.f; }
;     u32x4 xr0 = (u32x4){0u, 0u, 0u, 0u}, xr1 = (u32x4){0u, 0u, 0u, 0u};
;     ...
;     int it = lbid();
;     if (it < total) LRU_LOAD(it);
;     ...
;         {
;             const int seg = tid >> 7, d = (tid >> 6) & 1, j = tid & 63;
;             float h = 0.f, P = 1.f;
; #pragma unroll
;             for (int s = 0; s < 16; ++s) { const int st = seg * 16 + s, t = d ? 63 - st : st; const float a = As[(d * 64 + t) * 64 + j]; h = a * h + Bs[(d * 64 + t) * 64 + j]; P *= a; }
;             Pq[seg * 128 + (tid & 127)] = P; Hq[seg * 128 + (tid & 127)] = h;
;             __syncthreads();
;             if (PASS == 0) {
;                 if (tid < 128) { float hh = Hq[tid], PP = Pq[tid];
; #pragma unroll
;                     for (int q = 1; q < 4; ++q) { const float pq = Pq[q * 128 + tid]; hh = pq * hh + Hq[q * 128 + tid]; PP *= pq; }
;                     SA[so] = PP; SH[so] = hh; }
;             } else {
;                 float c = cin;
; #pragma unroll
;                 for (int q = 0; q < 3; ++q) if (q < seg) c = Pq[q * 128 + (tid & 127)] * c + Hq[q * 128 + (tid & 127)];
; #pragma unroll
;                 for (int s = 0; s < 16; ++s) { const int st = seg * 16 + s, t = d ? 63 - st : st; c = As[(d * 64 + t) * 64 + j] * c + Bs[(d * 64 + t) * 64 + j]; Bs[(d * 64 + t) * 64 + j] = c; }
	v_cndmask_b32_e32 v0, v13, v0, vcc
	v_lshl_or_b32 v24, v46, 12, v43
	v_lshlrev_b32_e32 v0, 6, v0
	v_add_lshl_u32 v0, v0, v24, 2
	v_add_u32_e32 v107, s5, v0
	v_add_u32_e32 v108, s4, v0
	v_or_b32_e32 v0, 2, v23
	v_sub_u32_e32 v13, 63, v0
	v_cndmask_b32_e32 v0, v13, v0, vcc
	v_lshlrev_b32_e32 v0, 6, v0
	v_add_lshl_u32 v0, v0, v24, 2
	v_add_u32_e32 v109, s5, v0
	v_add_u32_e32 v110, s4, v0
	v_or_b32_e32 v0, 3, v23
	v_sub_u32_e32 v13, 63, v0
	v_cndmask_b32_e32 v0, v13, v0, vcc
	v_lshlrev_b32_e32 v0, 6, v0
	v_add_lshl_u32 v0, v0, v24, 2
	v_add_u32_e32 v111, s5, v0
	v_add_u32_e32 v112, s4, v0
	v_or_b32_e32 v0, 4, v23
	v_sub_u32_e32 v13, 63, v0
	v_cndmask_b32_e32 v0, v13, v0, vcc
	v_lshlrev_b32_e32 v0, 6, v0
	v_add_lshl_u32 v0, v0, v24, 2
	v_add_u32_e32 v113, s5, v0
	v_add_u32_e32 v114, s4, v0
	v_or_b32_e32 v0, 5, v23
	v_sub_u32_e32 v13, 63, v0
	v_cndmask_b32_e32 v0, v13, v0, vcc
	v_lshlrev_b32_e32 v0, 6, v0
	v_add_lshl_u32 v0, v0, v24, 2
	v_add_u32_e32 v115, s5, v0
	v_add_u32_e32 v116, s4, v0
	v_or_b32_e32 v0, 6, v23
	v_sub_u32_e32 v13, 63, v0
	v_cndmask_b32_e32 v0, v13, v0, vcc
	v_lshlrev_b32_e32 v0, 6, v0
	v_add_lshl_u32 v0, v0, v24, 2
	v_add_u32_e32 v117, s5, v0
	v_add_u32_e32 v118, s4, v0
	v_or_b32_e32 v0, 7, v23
	v_sub_u32_e32 v13, 63, v0
	v_cndmask_b32_e32 v0, v13, v0, vcc
	v_lshlrev_b32_e32 v0, 6, v0
	v_add_lshl_u32 v0, v0, v24, 2
	v_add_u32_e32 v119, s5, v0
	v_add_u32_e32 v120, s4, v0
	v_or_b32_e32 v0, 8, v23
	v_sub_u32_e32 v13, 63, v0
	v_cndmask_b32_e32 v0, v13, v0, vcc
	v_lshlrev_b32_e32 v0, 6, v0
	v_add_lshl_u32 v0, v0, v24, 2
	v_add_u32_e32 v121, s5, v0
	v_add_u32_e32 v122, s4, v0
	v_or_b32_e32 v0, 9, v23
	v_sub_u32_e32 v13, 63, v0
	v_cndmask_b32_e32 v0, v13, v0, vcc
	v_lshlrev_b32_e32 v0, 6, v0
	v_add_lshl_u32 v0, v0, v24, 2
	v_add_u32_e32 v123, s5, v0
	v_add_u32_e32 v124, s4, v0
	v_or_b32_e32 v0, 10, v23
	v_sub_u32_e32 v13, 63, v0
	v_cndmask_b32_e32 v0, v13, v0, vcc
	v_lshlrev_b32_e32 v0, 6, v0
	v_add_lshl_u32 v0, v0, v24, 2
	v_add_u32_e32 v125, s5, v0
	v_add_u32_e32 v126, s4, v0
	v_or_b32_e32 v0, 11, v23
	v_sub_u32_e32 v13, 63, v0
	v_cndmask_b32_e32 v0, v13, v0, vcc
	v_lshlrev_b32_e32 v0, 6, v0
	v_add_lshl_u32 v0, v0, v24, 2
	v_add_u32_e32 v127, s5, v0
	v_add_u32_e32 v128, s4, v0
	v_or_b32_e32 v0, 12, v23
	v_sub_u32_e32 v13, 63, v0
	v_cndmask_b32_e32 v0, v13, v0, vcc
	v_lshlrev_b32_e32 v0, 6, v0
	v_add_lshl_u32 v0, v0, v24, 2
	v_add_u32_e32 v129, s5, v0
	v_add_u32_e32 v130, s4, v0
	v_or_b32_e32 v0, 13, v23
	v_sub_u32_e32 v13, 63, v0
	v_cndmask_b32_e32 v0, v13, v0, vcc
	v_lshlrev_b32_e32 v0, 6, v0
	v_add_lshl_u32 v0, v0, v24, 2
	v_add_u32_e32 v131, s5, v0
	v_add_u32_e32 v132, s4, v0
	v_or_b32_e32 v0, 14, v23
	v_sub_u32_e32 v13, 63, v0
	v_cndmask_b32_e32 v0, v13, v0, vcc
	v_lshlrev_b32_e32 v0, 6, v0
	v_add_lshl_u32 v0, v0, v24, 2
	v_add_u32_e32 v133, s5, v0
	v_add_u32_e32 v134, s4, v0
	v_or_b32_e32 v0, 15, v23
	v_sub_u32_e32 v13, 63, v0
	v_cndmask_b32_e32 v0, v13, v0, vcc
	v_lshlrev_b32_e32 v0, 6, v0
	v_add_lshl_u32 v0, v0, v24, 2
	v_readlane_b32 s1, v254, 4
	v_readlane_b32 s3, v254, 5
	v_sub_u32_e32 v25, 63, v23
	v_add_u32_e32 v135, s5, v0
	v_add_u32_e32 v136, s4, v0
	v_and_b32_e32 v0, 0x1fc, v10
	v_add_u32_e32 v48, s1, v10
	v_add_u32_e32 v49, s3, v10
	v_cndmask_b32_e32 v25, v25, v23, vcc
	v_lshlrev_b32_e32 v37, 2, v37
	v_add_u32_e32 v137, s3, v0
	v_add_u32_e32 v138, s1, v0
	v_or_b32_e32 v10, 0x200, v0
	v_or_b32_e32 v0, 0x400, v0
	v_lshlrev_b32_e32 v25, 6, v25
	v_mul_lo_u32 v32, v32, s0
	v_mul_lo_u32 v33, v33, s0
	v_mul_lo_u32 v34, v34, s0
	v_mul_lo_u32 v17, v17, s0
	v_add_u32_e32 v92, s5, v37
	v_add_u32_e32 v93, s4, v37
	v_or_b32_e32 v37, v19, v21
	v_or_b32_e32 v21, v20, v21
	v_add_u32_e32 v140, s1, v10
	v_add_u32_e32 v142, s1, v0
	v_readlane_b32 s0, v251, 10
	v_add_lshl_u32 v25, v25, v24, 2
	v_mul_u32_u24_e32 v18, 0x104, v18
	v_lshlrev_b32_e32 v37, 2, v37
	v_lshlrev_b32_e32 v21, 2, v21
	v_add_u32_e32 v141, s3, v0
	s_add_i32 s0, s0, s2
	v_mov_b32_e32 v0, v1
	v_lshl_add_u32 v44, v27, 7, v16
	v_add_u32_e32 v51, s5, v25
	v_add_u32_e32 v94, s5, v37
	v_add_u32_e32 v95, s4, v37
	v_add_u32_e32 v96, s5, v21
	v_add_u32_e32 v97, s4, v21
	v_add_u32_e32 v106, s4, v25
	v_cmp_lt_i32_e64 s[38:39], 0, v22
	v_cmp_lt_i32_e64 s[40:41], 1, v22
	v_add_u32_e32 v139, s3, v10
	v_cmp_lt_i32_e64 s[42:43], 2, v22
	s_lshl_b32 s3, s0, 2
	s_mov_b32 s5, -1
	v_add_u32_e32 v143, v16, v32
	v_add_u32_e32 v144, v16, v33
	v_add_u32_e32 v145, v16, v34
	v_add_u32_e32 v146, v16, v17
	v_add_u32_e32 v147, v12, v35
	v_add_u32_e32 v148, v11, v36
	v_add_u32_e32 v149, v15, v18
	v_mov_b32_e32 v160, 0
	v_mov_b32_e32 v161, 0
	v_mov_b32_e32 v162, 0
	v_mov_b32_e32 v163, 0
	v_mov_b64_e32 v[34:35], v[0:1]
	v_mov_b64_e32 v[36:37], v[0:1]
	v_mov_b32_e32 v164, 0
	v_mov_b32_e32 v165, 0
	v_mov_b32_e32 v166, 0
	v_mov_b32_e32 v167, 0
	v_mov_b32_e32 v168, 0
	v_mov_b32_e32 v169, 0
	v_mov_b32_e32 v170, 0
	v_mov_b32_e32 v171, 0
	v_readlane_b32 s64, v251, 24
	v_readlane_b32 s65, v251, 25
	v_readlane_b32 s66, v251, 26
	v_readlane_b32 s67, v251, 27
	v_readlane_b32 s72, v251, 32
	v_readlane_b32 s73, v251, 33
	v_readlane_b32 s74, v251, 34
	v_readlane_b32 s75, v251, 35
	v_readlane_b32 s1, v251, 11
	s_waitcnt vmcnt(0)
	s_branch .LBB0_200

; template <int PASS>
; __device__ void lru_items(const Params& p, unsigned char* shm, int l) {
;     ...
;     for (; it < total; it += G_) {
;         const int ck = it >> 4, n = it & 15, t0 = ck * 64;
;         *(u32x4*)(xraw + (tid >> 3) * 64 + (tid & 7) * 8) = xr0;
;         if (tid < 24) *(u32x4*)(xraw + (64 + (tid >> 3)) * 64 + (tid & 7) * 8) = xr1;
;         if (n != n_loaded) {
;             n_loaded = n;
; #pragma unroll
;             for (int i = 0; i < 4; ++i) { const int e = tid + 512 * i, mtx = e >> 9, rem = e & 511, j = rem >> 3, c8 = rem & 7;
;                 *(u32x4*)(wt + (mtx * 64 + j) * 72 + c8 * 8) = *(const u32x4*)(LWT + ((size_t)(mtx * 16 + n) * 64 + j) * 64 + c8 * 8); }
;             { const int ch = n * 64 + (tid & 63); c0 = cw[ch]; c1 = cw[1024 + ch]; c2 = cw[2048 + ch]; c3 = cw[3072 + ch]; cb = cbias[ch]; }
; #pragma unroll
;             for (int jt = 0; jt < 4; ++jt) { const int pi = (l * 2 + (w >> 2)) * 1024 + n * 64 + jt * 16 + fr; gba[jt] = p.in[7][pi]; gbx[jt] = p.in[9][pi]; gsp[jt] = -8.0f * log1pf(__expf(-p.in[10][pi])); }
.LBB0_200:
	ds_write_b128 v44, v[2:5]
	s_and_saveexec_b64 s[0:1], s[36:37]
	ds_write_b128 v44, v[6:9] offset:8192
	s_or_b64 exec, exec, s[0:1]
	s_and_b32 s4, s2, 15
	s_cmp_lg_u32 s4, s5
	s_mov_b64 s[0:1], -1
	s_cbranch_scc0 .LBB0_204
	v_or_b32_e32 v10, s4, v52
	v_or_b32_e32 v12, s4, v53
	s_lshl_b32 s48, s4, 6
	v_ashrrev_i32_e32 v11, 31, v10
	v_ashrrev_i32_e32 v13, 31, v12
	v_or_b32_e32 v22, s48, v45
	v_lshlrev_b64 v[10:11], 13, v[10:11]
	v_lshlrev_b64 v[12:13], 13, v[12:13]
	v_ashrrev_i32_e32 v23, 31, v22
	s_mov_b32 s0, s80
	s_mov_b32 s1, s92
	v_readlane_b32 s80, v251, 36
	v_lshl_add_u64 v[10:11], v[28:29], 0, v[10:11]
	v_lshl_add_u64 v[14:15], v[28:29], 0, v[12:13]
	v_lshlrev_b64 v[32:33], 2, v[22:23]
	v_readlane_b32 s84, v251, 40
	v_readlane_b32 s85, v251, 41
	global_load_dwordx4 v[10:13], v[10:11], off
	s_nop 0
	global_load_dwordx4 v[14:17], v[14:15], off
	v_lshl_add_u64 v[40:41], s[84:85], 0, v[32:33]
	global_load_dword v155, v[40:41], off
	global_load_dword v158, v[40:41], off offset:64
	v_or_b32_e32 v18, s4, v54
	v_or_b32_e32 v20, s4, v55
	v_ashrrev_i32_e32 v19, 31, v18
	v_ashrrev_i32_e32 v21, 31, v20
	v_lshlrev_b64 v[18:19], 13, v[18:19]
	v_lshlrev_b64 v[20:21], 13, v[20:21]
	v_lshl_add_u64 v[18:19], v[28:29], 0, v[18:19]
	v_lshl_add_u64 v[22:23], v[28:29], 0, v[20:21]
	global_load_dwordx4 v[18:21], v[18:19], off
	s_nop 0
	global_load_dwordx4 v[22:25], v[22:23], off
	v_or_b32_e32 v0, s48, v43
	v_lshlrev_b32_e32 v0, 2, v0
	s_mov_b32 s80, s0
	s_movk_i32 s0, 0x2000
	v_lshl_add_u64 v[38:39], s[60:61], 0, v[0:1]
	v_add_co_u32_e32 v152, vcc, s0, v38
	s_movk_i32 s0, 0x3000
	s_nop 0
	v_addc_co_u32_e32 v153, vcc, 0, v39, vcc
	v_add_co_u32_e32 v156, vcc, s0, v38
	global_load_dword v151, v0, s[60:61]
	global_load_dword v150, v0, s[62:63]
	v_addc_co_u32_e32 v157, vcc, 0, v39, vcc
	global_load_dword v154, v[152:153], off offset:-4096
	s_nop 0
	global_load_dword v153, v[152:153], off
	s_nop 0
	global_load_dword v152, v[156:157], off
	global_load_dword v0, v[40:41], off offset:128
	global_load_dword v180, v[40:41], off offset:192
	s_mov_b32 s0, 0x3f2aaaab
	s_mov_b32 s6, 0x3ecc95a3
	s_mov_b32 s8, 0x3e9b6dac
	s_mov_b32 s10, 0x3f2aaada
	s_mov_b32 s18, 0x3f317218
	s_mov_b32 s22, 0xb102e308
	v_readlane_b32 s92, v251, 48
	s_mov_b32 s92, s1
	s_mov_b32 s1, 0x7f800000
	s_mov_b32 s28, 0xc1000000
	v_readlane_b32 s64, v251, 20
	v_readlane_b32 s82, v251, 38
	v_readlane_b32 s83, v251, 39
	v_readlane_b32 s78, v251, 34
	v_readlane_b32 s79, v251, 35
	v_readlane_b32 s88, v251, 44
	v_readlane_b32 s89, v251, 45
	v_lshl_add_u64 v[38:39], s[78:79], 0, v[32:33]
	v_lshl_add_u64 v[32:33], s[82:83], 0, v[32:33]
	v_readlane_b32 s90, v251, 46
	v_readlane_b32 s91, v251, 47
	v_readlane_b32 s93, v251, 49
	v_readlane_b32 s94, v251, 50
	v_readlane_b32 s95, v251, 51
	v_readlane_b32 s88, v254, 27
	v_readlane_b32 s90, v254, 25
	v_readlane_b32 s81, v251, 37
	v_readlane_b32 s86, v251, 42
	v_readlane_b32 s87, v251, 43
	s_movk_i32 s94, 0x1000
	s_movk_i32 s95, 0x600
	v_readlane_b32 s89, v254, 28
	v_readlane_b32 s91, v254, 26
	v_readlane_b32 s93, v254, 24
	v_readlane_b32 s84, v254, 58
	v_readlane_b32 s65, v251, 21
	v_readlane_b32 s66, v251, 22
	v_readlane_b32 s67, v251, 23
	v_readlane_b32 s68, v251, 24
	s_waitcnt vmcnt(12)
	ds_write_b128 v143, v[10:13] offset:34560
	s_waitcnt vmcnt(11)
	ds_write_b128 v144, v[14:17] offset:34560
	s_waitcnt vmcnt(10)
	v_mul_f32_e32 v10, 0xbfb8aa3b, v155
	v_exp_f32_e32 v155, v10
	s_waitcnt vmcnt(9)
	v_mul_f32_e32 v11, 0xbfb8aa3b, v158
	v_exp_f32_e32 v158, v11
	s_waitcnt vmcnt(8)
	ds_write_b128 v145, v[18:21] offset:34560
	s_waitcnt vmcnt(7)
	ds_write_b128 v146, v[22:25] offset:34560
	v_add_f32_e32 v14, 1.0, v155
	v_frexp_mant_f32_e32 v17, v14
	v_cvt_f64_f32_e32 v[10:11], v14
	v_add_f32_e32 v15, 1.0, v158
	v_frexp_exp_i32_f64_e32 v10, v[10:11]
	v_cmp_gt_f32_e32 vcc, s0, v17
	v_add_f32_e32 v16, -1.0, v14
	v_frexp_mant_f32_e32 v19, v15
	v_cvt_f64_f32_e32 v[12:13], v15
	v_subbrev_co_u32_e32 v172, vcc, 0, v10, vcc
	v_add_f32_e32 v18, -1.0, v15
	v_sub_f32_e32 v20, v16, v14
	v_frexp_exp_i32_f64_e32 v12, v[12:13]
	v_cmp_gt_f32_e32 vcc, s0, v19
	v_sub_f32_e32 v16, v155, v16
	v_sub_f32_e32 v11, v18, v15
	v_add_f32_e32 v13, 1.0, v20
	v_subbrev_co_u32_e32 v173, vcc, 0, v12, vcc
	v_sub_f32_e32 v18, v158, v18
	v_add_f32_e32 v10, 1.0, v11
	v_add_f32_e32 v12, v16, v13
	v_sub_u32_e32 v13, 0, v172
	v_sub_u32_e32 v17, 0, v173
	v_add_f32_e32 v16, v18, v10
	v_ldexp_f32 v11, v14, v13
	v_ldexp_f32 v10, v15, v17
	v_pk_add_f32 v[14:15], v[10:11], 1.0 op_sel_hi:[1,0]
	v_ldexp_f32 v13, v12, v13
	v_ldexp_f32 v12, v16, v17
	v_pk_add_f32 v[16:17], v[10:11], -1.0 op_sel_hi:[1,0]
	v_pk_add_f32 v[18:19], v[14:15], -1.0 op_sel_hi:[1,0]
	v_pk_add_f32 v[20:21], v[16:17], 1.0 op_sel_hi:[1,0]
	v_pk_add_f32 v[18:19], v[10:11], v[18:19] neg_lo:[0,1] neg_hi:[0,1]
	v_pk_add_f32 v[10:11], v[10:11], v[20:21] neg_lo:[0,1] neg_hi:[0,1]
	v_pk_add_f32 v[18:19], v[12:13], v[18:19]
	v_pk_add_f32 v[10:11], v[12:13], v[10:11]
	v_pk_add_f32 v[12:13], v[14:15], v[18:19]
	v_pk_add_f32 v[20:21], v[16:17], v[10:11]
	v_rcp_f32_e32 v23, v13
	v_rcp_f32_e32 v22, v12
	v_pk_add_f32 v[16:17], v[20:21], v[16:17] neg_lo:[0,1] neg_hi:[0,1]
	v_pk_add_f32 v[14:15], v[12:13], v[14:15] neg_lo:[0,1] neg_hi:[0,1]
	v_pk_add_f32 v[10:11], v[10:11], v[16:17] neg_lo:[0,1] neg_hi:[0,1]
	v_pk_mul_f32 v[16:17], v[20:21], v[22:23]
	v_pk_add_f32 v[14:15], v[18:19], v[14:15] neg_lo:[0,1] neg_hi:[0,1]
	v_pk_mul_f32 v[18:19], v[12:13], v[16:17]
	v_cmp_neq_f32_e32 vcc, s1, v158
	v_pk_fma_f32 v[24:25], v[16:17], v[12:13], v[18:19] neg_lo:[0,0,1] neg_hi:[0,0,1]
	s_waitcnt vmcnt(1)
; template <int PASS>
; __device__ void lru_items(const Params& p, unsigned char* shm, int l) {
;     ...
;             { const int ch = n * 64 + (tid & 63); c0 = cw[ch]; c1 = cw[1024 + ch]; c2 = cw[2048 + ch]; c3 = cw[3072 + ch]; cb = cbias[ch]; }
; #pragma unroll
;             for (int jt = 0; jt < 4; ++jt) { const int pi = (l * 2 + (w >> 2)) * 1024 + n * 64 + jt * 16 + fr; gba[jt] = p.in[7][pi]; gbx[jt] = p.in[9][pi]; gsp[jt] = -8.0f * log1pf(__expf(-p.in[10][pi])); }
	v_mul_f32_e32 v0, 0xbfb8aa3b, v0
	v_pk_fma_f32 v[24:25], v[16:17], v[14:15], v[24:25]
	v_exp_f32_e32 v0, v0
	v_pk_add_f32 v[40:41], v[18:19], v[24:25]
	v_readlane_b32 s69, v251, 25
	v_pk_add_f32 v[156:157], v[20:21], v[40:41] neg_lo:[0,1] neg_hi:[0,1]
	v_pk_add_f32 v[18:19], v[40:41], v[18:19] neg_lo:[0,1] neg_hi:[0,1]
	v_pk_add_f32 v[20:21], v[20:21], v[156:157] neg_lo:[0,1] neg_hi:[0,1]
	v_pk_add_f32 v[18:19], v[18:19], v[24:25] neg_lo:[0,1] neg_hi:[0,1]
	v_pk_add_f32 v[20:21], v[20:21], v[40:41] neg_lo:[0,1] neg_hi:[0,1]
	v_readlane_b32 s70, v251, 26
	v_pk_add_f32 v[10:11], v[10:11], v[20:21]
	v_readlane_b32 s71, v251, 27
	v_pk_add_f32 v[10:11], v[18:19], v[10:11]
	v_readlane_b32 s72, v251, 28
	v_pk_add_f32 v[18:19], v[156:157], v[10:11]
	v_readlane_b32 s73, v251, 29
	v_pk_mul_f32 v[20:21], v[22:23], v[18:19]
	v_pk_add_f32 v[24:25], v[156:157], v[18:19] neg_lo:[0,1] neg_hi:[0,1]
	v_pk_mul_f32 v[40:41], v[12:13], v[20:21]
	v_pk_add_f32 v[10:11], v[10:11], v[24:25]
	v_pk_fma_f32 v[12:13], v[20:21], v[12:13], v[40:41] neg_lo:[0,0,1] neg_hi:[0,0,1]
	v_readlane_b32 s74, v251, 30
	v_pk_fma_f32 v[12:13], v[20:21], v[14:15], v[12:13]
	v_readlane_b32 s75, v251, 31
	v_pk_add_f32 v[14:15], v[40:41], v[12:13]
	v_readlane_b32 s76, v251, 32
	v_pk_add_f32 v[24:25], v[14:15], v[40:41] neg_lo:[0,1] neg_hi:[0,1]
	v_pk_add_f32 v[40:41], v[18:19], v[14:15] neg_lo:[0,1] neg_hi:[0,1]
	v_pk_add_f32 v[12:13], v[24:25], v[12:13] neg_lo:[0,1] neg_hi:[0,1]
	v_pk_add_f32 v[18:19], v[18:19], v[40:41] neg_lo:[0,1] neg_hi:[0,1]
	v_readlane_b32 s77, v251, 33
	v_pk_add_f32 v[14:15], v[18:19], v[14:15] neg_lo:[0,1] neg_hi:[0,1]
	v_mov_b64_e32 v[18:19], s[6:7]
	v_pk_add_f32 v[10:11], v[10:11], v[14:15]
	s_mov_b32 s6, 0x33800000
	v_pk_add_f32 v[10:11], v[12:13], v[10:11]
	v_pk_add_f32 v[12:13], v[16:17], v[20:21]
	v_pk_add_f32 v[10:11], v[40:41], v[10:11]
	v_pk_add_f32 v[14:15], v[12:13], v[16:17] neg_lo:[0,1] neg_hi:[0,1]
	v_pk_mul_f32 v[10:11], v[22:23], v[10:11]
	v_pk_add_f32 v[14:15], v[20:21], v[14:15] neg_lo:[0,1] neg_hi:[0,1]
	v_cvt_f32_i32_e32 v23, v172
	v_pk_add_f32 v[10:11], v[14:15], v[10:11]
	v_cvt_f32_i32_e32 v22, v173
	v_pk_add_f32 v[14:15], v[12:13], v[10:11]
	s_movk_i32 s82, 0x60
	v_pk_mul_f32 v[16:17], v[14:15], v[14:15]
	v_pk_add_f32 v[12:13], v[14:15], v[12:13] neg_lo:[0,1] neg_hi:[0,1]
	v_pk_fma_f32 v[20:21], v[16:17], s[8:9], v[18:19] op_sel_hi:[1,0,0]
	v_pk_add_f32 v[10:11], v[10:11], v[12:13] neg_lo:[0,1] neg_hi:[0,1]
	v_ldexp_f32 v13, v15, 1
	v_pk_fma_f32 v[20:21], v[16:17], v[20:21], s[10:11] op_sel_hi:[1,1,0]
	v_ldexp_f32 v12, v14, 1
	v_pk_mul_f32 v[14:15], v[14:15], v[16:17]
	v_pk_mul_f32 v[16:17], v[22:23], s[18:19] op_sel_hi:[1,0]
	v_pk_mul_f32 v[14:15], v[14:15], v[20:21]
	v_pk_fma_f32 v[40:41], v[22:23], s[18:19], v[16:17] op_sel_hi:[1,0,1] neg_lo:[0,0,1] neg_hi:[0,0,1]
	v_pk_add_f32 v[20:21], v[12:13], v[14:15]
	v_ldexp_f32 v11, v11, 1
	v_pk_add_f32 v[12:13], v[20:21], v[12:13] neg_lo:[0,1] neg_hi:[0,1]
	v_pk_fma_f32 v[22:23], v[22:23], s[22:23], v[40:41] op_sel_hi:[1,0,1]
	v_pk_add_f32 v[12:13], v[14:15], v[12:13] neg_lo:[0,1] neg_hi:[0,1]
	v_ldexp_f32 v24, v10, 1
	v_mov_b32_e32 v14, v16
	v_mov_b32_e32 v15, v13
	v_mov_b32_e32 v10, v22
	v_mov_b32_e32 v25, v11
	v_pk_add_f32 v[14:15], v[14:15], v[10:11]
	v_pk_add_f32 v[10:11], v[24:25], v[12:13]
	v_mov_b32_e32 v13, v21
	v_mov_b32_e32 v25, v11
	v_pk_add_f32 v[40:41], v[16:17], v[22:23]
	v_pk_add_f32 v[12:13], v[24:25], v[12:13]
	v_pk_add_f32 v[24:25], v[20:21], v[10:11]
	v_mov_b32_e32 v174, v20
	v_pk_add_f32 v[156:157], v[40:41], v[24:25]
	v_mov_b32_e32 v172, v24
	v_mov_b32_e32 v173, v157
	v_mov_b32_e32 v175, v41
	v_pk_add_f32 v[172:173], v[172:173], v[174:175] neg_lo:[0,1] neg_hi:[0,1]
	v_mov_b32_e32 v174, v40
	v_mov_b32_e32 v175, v157
	v_mov_b32_e32 v176, v16
	v_mov_b32_e32 v177, v173
	v_pk_add_f32 v[174:175], v[174:175], v[176:177] neg_lo:[0,1] neg_hi:[0,1]
	v_mov_b32_e32 v177, v41
	v_mov_b32_e32 v178, v156
	v_mov_b32_e32 v179, v41
	v_mov_b32_e32 v41, v17
	v_mov_b32_e32 v176, v22
	v_pk_add_f32 v[16:17], v[178:179], v[40:41] neg_lo:[0,1] neg_hi:[0,1]
	v_pk_add_f32 v[176:177], v[176:177], v[174:175] neg_lo:[0,1] neg_hi:[0,1]
	v_mov_b32_e32 v175, v17
	v_pk_add_f32 v[40:41], v[22:23], v[174:175] neg_lo:[0,1] neg_hi:[0,1]
	v_pk_add_f32 v[174:175], v[24:25], v[20:21] neg_lo:[0,1] neg_hi:[0,1]
	v_pk_add_f32 v[12:13], v[12:13], v[172:173] neg_lo:[0,1] neg_hi:[0,1]
	v_mov_b32_e32 v172, v156
	v_mov_b32_e32 v173, v25
	v_mov_b32_e32 v20, v16
	v_pk_add_f32 v[20:21], v[172:173], v[20:21] neg_lo:[0,1] neg_hi:[0,1]
	v_mov_b32_e32 v25, v23
	v_pk_add_f32 v[14:15], v[14:15], v[20:21] neg_lo:[0,1] neg_hi:[0,1]
	v_pk_add_f32 v[16:17], v[24:25], v[16:17] neg_lo:[0,1] neg_hi:[0,1]
	v_pk_add_f32 v[22:23], v[12:13], v[176:177]
	v_mov_b32_e32 v177, v17
	v_mov_b32_e32 v13, v15
	v_pk_add_f32 v[20:21], v[16:17], v[14:15]
	v_pk_add_f32 v[12:13], v[176:177], v[12:13]
	v_mov_b32_e32 v14, v22
	v_pk_add_f32 v[12:13], v[12:13], v[40:41] neg_lo:[0,1] neg_hi:[0,1]
	v_mov_b32_e32 v15, v21
	v_pk_add_f32 v[10:11], v[10:11], v[174:175] neg_lo:[0,1] neg_hi:[0,1]
	v_pk_add_f32 v[14:15], v[14:15], v[12:13] neg_lo:[0,1] neg_hi:[0,1]
	v_pk_add_f32 v[10:11], v[10:11], v[12:13] neg_lo:[0,1] neg_hi:[0,1]
	v_pk_add_f32 v[14:15], v[176:177], v[14:15] neg_lo:[0,1] neg_hi:[0,1]
	v_pk_add_f32 v[12:13], v[20:21], v[22:23]
	v_pk_add_f32 v[10:11], v[10:11], v[14:15]
	v_pk_add_f32 v[14:15], v[156:157], v[12:13]
	s_nop 0
	v_pk_add_f32 v[16:17], v[14:15], v[156:157] neg_lo:[0,1] neg_hi:[0,1]
	s_nop 0
	v_pk_add_f32 v[12:13], v[12:13], v[16:17] neg_lo:[0,1] neg_hi:[0,1]
	s_nop 0
	v_pk_add_f32 v[10:11], v[10:11], v[12:13]
	v_add_f32_e32 v12, 1.0, v0
	v_pk_add_f32 v[10:11], v[14:15], v[10:11]
	v_frexp_mant_f32_e32 v14, v12
	v_cndmask_b32_e32 v10, v237, v10, vcc
	v_cmp_neq_f32_e32 vcc, s1, v155
	s_nop 1
	v_cndmask_b32_e32 v11, v237, v11, vcc
	v_cmp_ngt_f32_e32 vcc, -1.0, v155
	s_nop 1
	v_cndmask_b32_e32 v11, v238, v11, vcc
	v_cmp_ngt_f32_e32 vcc, -1.0, v158
	s_nop 1
	v_cndmask_b32_e32 v10, v238, v10, vcc
	v_cmp_neq_f32_e32 vcc, -1.0, v158
	s_nop 1
	v_cndmask_b32_e32 v10, v239, v10, vcc
	v_cmp_neq_f32_e32 vcc, -1.0, v155
	s_nop 1
	v_cndmask_b32_e32 v11, v239, v11, vcc
	v_cmp_lt_f32_e64 vcc, |v155|, s6
	s_nop 1
	v_cndmask_b32_e32 v11, v11, v155, vcc
	v_cmp_lt_f32_e64 vcc, |v158|, s6
	s_nop 1
	v_cndmask_b32_e32 v10, v10, v158, vcc
	v_pk_mul_f32 v[22:23], v[10:11], s[28:29] op_sel_hi:[1,0]
	v_add_f32_e32 v10, -1.0, v12
	v_sub_f32_e32 v11, v10, v12
	v_add_f32_e32 v11, 1.0, v11
	v_sub_f32_e32 v10, v0, v10
	v_add_f32_e32 v13, v10, v11
	v_cvt_f64_f32_e32 v[10:11], v12
	v_frexp_exp_i32_f64_e32 v10, v[10:11]
	v_cmp_gt_f32_e32 vcc, s0, v14
	global_load_dword v157, v[38:39], off
	global_load_dword v158, v[38:39], off offset:64
	global_load_dword v40, v[38:39], off offset:128
	global_load_dword v41, v[38:39], off offset:192
	v_subbrev_co_u32_e32 v178, vcc, 0, v10, vcc
	v_sub_u32_e32 v10, 0, v178
	v_ldexp_f32 v11, v12, v10
	v_ldexp_f32 v13, v13, v10
	s_waitcnt vmcnt(4)
; template <int PASS>
; __device__ void lru_items(const Params& p, unsigned char* shm, int l) {
;     ...
;             { const int ch = n * 64 + (tid & 63); c0 = cw[ch]; c1 = cw[1024 + ch]; c2 = cw[2048 + ch]; c3 = cw[3072 + ch]; cb = cbias[ch]; }
; #pragma unroll
;             for (int jt = 0; jt < 4; ++jt) { const int pi = (l * 2 + (w >> 2)) * 1024 + n * 64 + jt * 16 + fr; gba[jt] = p.in[7][pi]; gbx[jt] = p.in[9][pi]; gsp[jt] = -8.0f * log1pf(__expf(-p.in[10][pi])); }
	v_mul_f32_e32 v10, 0xbfb8aa3b, v180
	v_exp_f32_e32 v182, v10
	global_load_dword v155, v[32:33], off
	global_load_dword v156, v[32:33], off offset:64
	global_load_dword v38, v[32:33], off offset:128
	global_load_dword v39, v[32:33], off offset:192
	v_add_f32_e32 v10, 1.0, v182
	v_add_f32_e32 v12, -1.0, v10
	v_sub_f32_e32 v14, v12, v10
	v_add_f32_e32 v14, 1.0, v14
	v_sub_f32_e32 v12, v182, v12
	v_add_f32_e32 v12, v12, v14
	v_frexp_mant_f32_e32 v16, v10
	v_cvt_f64_f32_e32 v[14:15], v10
	v_frexp_exp_i32_f64_e32 v14, v[14:15]
	v_cmp_gt_f32_e32 vcc, s0, v16
	s_nop 1
	v_subbrev_co_u32_e32 v179, vcc, 0, v14, vcc
	v_sub_u32_e32 v14, 0, v179
	v_ldexp_f32 v10, v10, v14
	v_ldexp_f32 v12, v12, v14
	v_pk_add_f32 v[14:15], v[10:11], 1.0 op_sel_hi:[1,0]
	v_pk_add_f32 v[32:33], v[10:11], -1.0 op_sel_hi:[1,0]
	v_pk_add_f32 v[16:17], v[14:15], -1.0 op_sel_hi:[1,0]
	v_pk_add_f32 v[172:173], v[32:33], 1.0 op_sel_hi:[1,0]
	v_pk_add_f32 v[16:17], v[10:11], v[16:17] neg_lo:[0,1] neg_hi:[0,1]
	v_pk_add_f32 v[10:11], v[10:11], v[172:173] neg_lo:[0,1] neg_hi:[0,1]
	v_pk_add_f32 v[16:17], v[12:13], v[16:17]
	v_pk_add_f32 v[10:11], v[12:13], v[10:11]
	v_pk_add_f32 v[20:21], v[14:15], v[16:17]
	v_pk_add_f32 v[12:13], v[32:33], v[10:11]
	v_rcp_f32_e32 v25, v21
	v_rcp_f32_e32 v24, v20
	v_pk_add_f32 v[14:15], v[20:21], v[14:15] neg_lo:[0,1] neg_hi:[0,1]
	v_pk_add_f32 v[32:33], v[12:13], v[32:33] neg_lo:[0,1] neg_hi:[0,1]
	v_pk_add_f32 v[14:15], v[16:17], v[14:15] neg_lo:[0,1] neg_hi:[0,1]
	v_pk_mul_f32 v[16:17], v[12:13], v[24:25]
	v_pk_add_f32 v[10:11], v[10:11], v[32:33] neg_lo:[0,1] neg_hi:[0,1]
	v_pk_mul_f32 v[32:33], v[20:21], v[16:17]
	v_cmp_neq_f32_e32 vcc, s1, v182
	v_pk_fma_f32 v[172:173], v[16:17], v[20:21], v[32:33] neg_lo:[0,0,1] neg_hi:[0,0,1]
	s_nop 0
	v_pk_fma_f32 v[172:173], v[16:17], v[14:15], v[172:173]
	s_nop 0
	v_pk_add_f32 v[174:175], v[32:33], v[172:173]
	s_nop 0
	v_pk_add_f32 v[176:177], v[12:13], v[174:175] neg_lo:[0,1] neg_hi:[0,1]
	v_pk_add_f32 v[32:33], v[174:175], v[32:33] neg_lo:[0,1] neg_hi:[0,1]
	v_pk_add_f32 v[12:13], v[12:13], v[176:177] neg_lo:[0,1] neg_hi:[0,1]
	s_nop 0
	v_pk_add_f32 v[12:13], v[12:13], v[174:175] neg_lo:[0,1] neg_hi:[0,1]
	s_nop 0
	v_pk_add_f32 v[10:11], v[10:11], v[12:13]
	v_pk_add_f32 v[12:13], v[32:33], v[172:173] neg_lo:[0,1] neg_hi:[0,1]
	s_nop 0
	v_pk_add_f32 v[10:11], v[12:13], v[10:11]
	s_nop 0
	v_pk_add_f32 v[12:13], v[176:177], v[10:11]
	s_nop 0
	v_pk_mul_f32 v[32:33], v[24:25], v[12:13]
	s_nop 0
	v_pk_mul_f32 v[172:173], v[20:21], v[32:33]
	s_nop 0
	v_pk_fma_f32 v[20:21], v[32:33], v[20:21], v[172:173] neg_lo:[0,0,1] neg_hi:[0,0,1]
	s_nop 0
	v_pk_fma_f32 v[14:15], v[32:33], v[14:15], v[20:21]
	v_pk_add_f32 v[20:21], v[176:177], v[12:13] neg_lo:[0,1] neg_hi:[0,1]
	s_nop 0
	v_pk_add_f32 v[10:11], v[10:11], v[20:21]
	v_pk_add_f32 v[20:21], v[172:173], v[14:15]
	s_nop 0
	v_pk_add_f32 v[174:175], v[12:13], v[20:21] neg_lo:[0,1] neg_hi:[0,1]
	v_pk_add_f32 v[172:173], v[20:21], v[172:173] neg_lo:[0,1] neg_hi:[0,1]
	v_pk_add_f32 v[12:13], v[12:13], v[174:175] neg_lo:[0,1] neg_hi:[0,1]
	s_nop 0
	v_pk_add_f32 v[12:13], v[12:13], v[20:21] neg_lo:[0,1] neg_hi:[0,1]
	v_cvt_f32_i32_e32 v21, v178
	v_pk_add_f32 v[10:11], v[10:11], v[12:13]
	v_pk_add_f32 v[12:13], v[172:173], v[14:15] neg_lo:[0,1] neg_hi:[0,1]
	v_cvt_f32_i32_e32 v20, v179
	v_pk_add_f32 v[10:11], v[12:13], v[10:11]
	v_pk_add_f32 v[12:13], v[16:17], v[32:33]
	v_pk_add_f32 v[10:11], v[174:175], v[10:11]
	v_pk_add_f32 v[14:15], v[12:13], v[16:17] neg_lo:[0,1] neg_hi:[0,1]
	v_pk_mul_f32 v[10:11], v[24:25], v[10:11]
	v_pk_add_f32 v[14:15], v[32:33], v[14:15] neg_lo:[0,1] neg_hi:[0,1]
	s_nop 0
	v_pk_add_f32 v[10:11], v[14:15], v[10:11]
	s_nop 0
	v_pk_add_f32 v[14:15], v[12:13], v[10:11]
	s_nop 0
	v_pk_mul_f32 v[16:17], v[14:15], v[14:15]
	v_pk_add_f32 v[12:13], v[14:15], v[12:13] neg_lo:[0,1] neg_hi:[0,1]
	v_pk_fma_f32 v[18:19], v[16:17], s[8:9], v[18:19] op_sel_hi:[1,0,0]
	v_pk_add_f32 v[10:11], v[10:11], v[12:13] neg_lo:[0,1] neg_hi:[0,1]
	v_ldexp_f32 v13, v15, 1
	v_pk_fma_f32 v[18:19], v[16:17], v[18:19], s[10:11] op_sel_hi:[1,1,0]
	v_ldexp_f32 v12, v14, 1
	v_pk_mul_f32 v[14:15], v[14:15], v[16:17]
; __device__ __forceinline__ float sigm(float x) { return __builtin_amdgcn_rcpf(1.0f + __expf(-x)); }
; template <int PASS>
; __device__ void lru_items(const Params& p, unsigned char* shm, int l) {
;     ...
;             { const int ch = n * 64 + (tid & 63); c0 = cw[ch]; c1 = cw[1024 + ch]; c2 = cw[2048 + ch]; c3 = cw[3072 + ch]; cb = cbias[ch]; }
; #pragma unroll
;             for (int jt = 0; jt < 4; ++jt) { const int pi = (l * 2 + (w >> 2)) * 1024 + n * 64 + jt * 16 + fr; gba[jt] = p.in[7][pi]; gbx[jt] = p.in[9][pi]; gsp[jt] = -8.0f * log1pf(__expf(-p.in[10][pi])); }
;     ...
;                   const float r = sigm(accr[i] + gba[jt]), ig = sigm(acci[i] + gbx[jt]), a = __expf(r * gsp[jt]);
	v_pk_mul_f32 v[16:17], v[20:21], s[18:19] op_sel_hi:[1,0]
	v_pk_mul_f32 v[14:15], v[14:15], v[18:19]
	v_pk_fma_f32 v[32:33], v[20:21], s[18:19], v[16:17] op_sel_hi:[1,0,1] neg_lo:[0,0,1] neg_hi:[0,0,1]
	v_pk_add_f32 v[18:19], v[12:13], v[14:15]
	v_ldexp_f32 v11, v11, 1
	v_pk_add_f32 v[12:13], v[18:19], v[12:13] neg_lo:[0,1] neg_hi:[0,1]
	v_pk_fma_f32 v[20:21], v[20:21], s[22:23], v[32:33] op_sel_hi:[1,0,1]
	v_pk_add_f32 v[12:13], v[14:15], v[12:13] neg_lo:[0,1] neg_hi:[0,1]
	v_ldexp_f32 v24, v10, 1
	v_mov_b32_e32 v14, v16
	v_mov_b32_e32 v15, v13
	v_mov_b32_e32 v10, v20
	v_mov_b32_e32 v25, v11
	v_pk_add_f32 v[14:15], v[14:15], v[10:11]
	v_pk_add_f32 v[10:11], v[24:25], v[12:13]
	v_mov_b32_e32 v13, v19
	v_mov_b32_e32 v25, v11
	v_pk_add_f32 v[32:33], v[16:17], v[20:21]
	v_pk_add_f32 v[12:13], v[24:25], v[12:13]
	v_pk_add_f32 v[24:25], v[18:19], v[10:11]
	v_mov_b32_e32 v176, v18
	v_pk_add_f32 v[172:173], v[32:33], v[24:25]
	v_mov_b32_e32 v174, v24
	v_mov_b32_e32 v175, v173
	v_mov_b32_e32 v177, v33
	v_pk_add_f32 v[174:175], v[174:175], v[176:177] neg_lo:[0,1] neg_hi:[0,1]
	v_mov_b32_e32 v176, v32
	v_mov_b32_e32 v177, v173
	v_mov_b32_e32 v178, v16
	v_mov_b32_e32 v179, v175
	v_pk_add_f32 v[176:177], v[176:177], v[178:179] neg_lo:[0,1] neg_hi:[0,1]
	v_mov_b32_e32 v179, v33
	v_mov_b32_e32 v180, v172
	v_mov_b32_e32 v181, v33
	v_mov_b32_e32 v33, v17
	v_mov_b32_e32 v178, v20
	v_pk_add_f32 v[16:17], v[180:181], v[32:33] neg_lo:[0,1] neg_hi:[0,1]
	v_pk_add_f32 v[178:179], v[178:179], v[176:177] neg_lo:[0,1] neg_hi:[0,1]
	v_mov_b32_e32 v177, v17
	v_pk_add_f32 v[32:33], v[20:21], v[176:177] neg_lo:[0,1] neg_hi:[0,1]
	v_pk_add_f32 v[176:177], v[24:25], v[18:19] neg_lo:[0,1] neg_hi:[0,1]
	v_pk_add_f32 v[12:13], v[12:13], v[174:175] neg_lo:[0,1] neg_hi:[0,1]
	v_mov_b32_e32 v174, v172
	v_mov_b32_e32 v175, v25
	v_mov_b32_e32 v18, v16
	v_pk_add_f32 v[18:19], v[174:175], v[18:19] neg_lo:[0,1] neg_hi:[0,1]
	v_mov_b32_e32 v25, v21
	v_pk_add_f32 v[14:15], v[14:15], v[18:19] neg_lo:[0,1] neg_hi:[0,1]
	v_pk_add_f32 v[16:17], v[24:25], v[16:17] neg_lo:[0,1] neg_hi:[0,1]
	v_pk_add_f32 v[20:21], v[12:13], v[178:179]
	v_mov_b32_e32 v179, v17
	v_mov_b32_e32 v13, v15
	v_pk_add_f32 v[18:19], v[16:17], v[14:15]
	v_pk_add_f32 v[12:13], v[178:179], v[12:13]
	v_mov_b32_e32 v14, v20
	v_pk_add_f32 v[12:13], v[12:13], v[32:33] neg_lo:[0,1] neg_hi:[0,1]
	v_mov_b32_e32 v15, v19
	v_pk_add_f32 v[10:11], v[10:11], v[176:177] neg_lo:[0,1] neg_hi:[0,1]
	v_pk_add_f32 v[14:15], v[14:15], v[12:13] neg_lo:[0,1] neg_hi:[0,1]
	v_pk_add_f32 v[10:11], v[10:11], v[12:13] neg_lo:[0,1] neg_hi:[0,1]
	v_pk_add_f32 v[14:15], v[178:179], v[14:15] neg_lo:[0,1] neg_hi:[0,1]
	v_pk_add_f32 v[12:13], v[18:19], v[20:21]
	v_pk_add_f32 v[10:11], v[10:11], v[14:15]
	v_pk_add_f32 v[14:15], v[172:173], v[12:13]
	s_nop 0
	v_pk_add_f32 v[16:17], v[14:15], v[172:173] neg_lo:[0,1] neg_hi:[0,1]
	s_nop 0
	v_pk_add_f32 v[12:13], v[12:13], v[16:17] neg_lo:[0,1] neg_hi:[0,1]
	s_nop 0
	v_pk_add_f32 v[10:11], v[10:11], v[12:13]
	s_nop 0
	v_pk_add_f32 v[10:11], v[14:15], v[10:11]
	s_nop 0
	v_cndmask_b32_e32 v10, v237, v10, vcc
	v_cmp_neq_f32_e32 vcc, s1, v0
	s_mov_b64 s[0:1], 0
	s_nop 0
	v_cndmask_b32_e32 v11, v237, v11, vcc
	v_cmp_ngt_f32_e32 vcc, -1.0, v0
	s_nop 1
	v_cndmask_b32_e32 v11, v238, v11, vcc
	v_cmp_ngt_f32_e32 vcc, -1.0, v182
	s_nop 1
	v_cndmask_b32_e32 v10, v238, v10, vcc
	v_cmp_neq_f32_e32 vcc, -1.0, v182
	s_nop 1
	v_cndmask_b32_e32 v10, v239, v10, vcc
	v_cmp_neq_f32_e32 vcc, -1.0, v0
	s_nop 1
	v_cndmask_b32_e32 v11, v239, v11, vcc
	v_cmp_lt_f32_e64 vcc, |v0|, s6
	s_nop 1
	v_cndmask_b32_e32 v11, v11, v0, vcc
	v_cmp_lt_f32_e64 vcc, |v182|, s6
	s_nop 1
	v_cndmask_b32_e32 v10, v10, v182, vcc
	v_pk_mul_f32 v[24:25], v[10:11], s[28:29] op_sel_hi:[1,0]
	s_waitcnt vmcnt(0)
	v_mul_f32_e32 v155, 0xbfb8aa3b, v155
	v_mul_f32_e32 v156, 0xbfb8aa3b, v156
	v_mul_f32_e32 v157, 0xbfb8aa3b, v157
	v_mul_f32_e32 v158, 0xbfb8aa3b, v158
	v_mul_f32_e32 v38, 0xbfb8aa3b, v38
	v_mul_f32_e32 v39, 0xbfb8aa3b, v39
	v_mul_f32_e32 v40, 0xbfb8aa3b, v40
	v_mul_f32_e32 v41, 0xbfb8aa3b, v41
	v_mul_f32_e32 v22, 0x3fb8aa3b, v22
	v_mul_f32_e32 v23, 0x3fb8aa3b, v23
	v_mul_f32_e32 v24, 0x3fb8aa3b, v24
	v_mul_f32_e32 v25, 0x3fb8aa3b, v25

; __device__ __forceinline__ int ltid(int wave) { int t = (wave << 6) | (int)__builtin_amdgcn_mbcnt_hi(~0u, __builtin_amdgcn_mbcnt_lo(~0u, 0u)); asm volatile("" : "+v"(t)); return t; }
; template <int PASS>
; __device__ void lru_items(const Params& p, unsigned char* shm, int l) {
;     ...
;     const bf16_t* XL = (const bf16_t*)(p.ws + B_XL); bf16_t* GL = (bf16_t*)(p.ws + B_GL); const bf16_t* LWT = (const bf16_t*)(p.ws + SM_LWT);
;     float* SA = (float*)(p.ws + SM_SA); float* SH = (float*)(p.ws + SM_SH); const float* CIN = (const float*)(p.ws + SM_CIN);
;     const float* cw = p.in[4] + l * 4096; const float* cbias = p.in[5] + l * 1024;
;     const int tid = ltid(p.wave), lane = tid & 63, w = tid >> 6, fr = lane & 15, fq = lane >> 4, G_ = gridDim.x, total = NCHK * 16;
;     int n_loaded = -1;
;     float c0 = 0.f, c1 = 0.f, c2 = 0.f, c3 = 0.f, cb = 0.f, gba[4], gbx[4], gsp[4];
; #pragma unroll
;     for (int jt = 0; jt < 4; ++jt) { gba[jt] = 0.f; gbx[jt] = 0.f; gsp[jt] = 0.f; }
;     u32x4 xr0 = (u32x4){0u, 0u, 0u, 0u}, xr1 = (u32x4){0u, 0u, 0u, 0u};
;     ...
;     int it = lbid();
;     if (it < total) LRU_LOAD(it);
;     for (; it < total; it += G_) {
;         const int ck = it >> 4, n = it & 15, t0 = ck * 64;
;         *(u32x4*)(xraw + (tid >> 3) * 64 + (tid & 7) * 8) = xr0;
;         if (tid < 24) *(u32x4*)(xraw + (64 + (tid >> 3)) * 64 + (tid & 7) * 8) = xr1;
;         if (n != n_loaded) {
;             n_loaded = n;
; #pragma unroll
;             for (int i = 0; i < 4; ++i) { const int e = tid + 512 * i, mtx = e >> 9, rem = e & 511, j = rem >> 3, c8 = rem & 7;
;                 *(u32x4*)(wt + (mtx * 64 + j) * 72 + c8 * 8) = *(const u32x4*)(LWT + ((size_t)(mtx * 16 + n) * 64 + j) * 64 + c8 * 8); }
;             { const int ch = n * 64 + (tid & 63); c0 = cw[ch]; c1 = cw[1024 + ch]; c2 = cw[2048 + ch]; c3 = cw[3072 + ch]; cb = cbias[ch]; }
; #pragma unroll
;             for (int jt = 0; jt < 4; ++jt) { const int pi = (l * 2 + (w >> 2)) * 1024 + n * 64 + jt * 16 + fr; gba[jt] = p.in[7][pi]; gbx[jt] = p.in[9][pi]; gsp[jt] = -8.0f * log1pf(__expf(-p.in[10][pi])); }
;         }
;         u32x4 glv = (u32x4){0u, 0u, 0u, 0u}; float cin = 0.f;
;         const size_t go = (size_t)(t0 + (tid >> 3)) * 1024 + n * 64 + (tid & 7) * 8;
;         const size_t so = (size_t)(ck * 2 + ((tid >> 6) & 1)) * 1024 + n * 64 + (tid & 63);
.LBB0_294:
	s_or_b64 exec, exec, s[0:1]
	v_readlane_b32 s0, v254, 43
	v_readlane_b32 s1, v254, 44
	s_mov_b32 s6, s0
	s_lshl_b32 s0, s0, 12
	s_ashr_i32 s1, s0, 31
	s_lshl_b32 s4, s6, 10
	v_readlane_b32 s60, v251, 20
	s_ashr_i32 s5, s4, 31
	s_lshl_b64 s[0:1], s[0:1], 2
	v_readlane_b32 s68, v251, 28
	v_readlane_b32 s69, v251, 29
	s_add_u32 s42, s68, s0
	v_readlane_b32 s70, v251, 30
	s_addc_u32 s43, s69, s1
	s_lshl_b64 s[0:1], s[4:5], 2
	v_readlane_b32 s71, v251, 31
	s_add_u32 s46, s70, s0
	s_addc_u32 s47, s71, s1
	v_lshlrev_b32_e32 v0, 3, v13
	v_bfe_u32 v19, v13, 3, 6
	v_readlane_b32 s0, v252, 11
	v_and_b32_e32 v28, 56, v0
	v_lshlrev_b32_e32 v0, 7, v19
	v_readlane_b32 s1, v252, 12
	v_lshlrev_b32_e32 v10, 1, v28
	v_mov_b32_e32 v11, v1
	v_lshl_add_u64 v[14:15], s[0:1], 0, v[0:1]
	v_lshlrev_b32_e32 v0, 2, v13
	v_add_u32_e32 v18, 0, v10
	v_lshl_add_u64 v[30:31], v[14:15], 0, v[10:11]
	v_and_b32_e32 v10, 0xfffffc00, v0
	v_and_b32_e32 v26, 63, v13
	v_and_b32_e32 v16, 15, v13
	v_lshl_add_u32 v10, s6, 11, v10
	s_movk_i32 s0, 0x80
	v_ashrrev_i32_e32 v17, 6, v13
	v_or_b32_e32 v42, v10, v16
	v_lshlrev_b32_e32 v10, 1, v26
	v_ashrrev_i32_e32 v15, 8, v13
	v_and_b32_e32 v22, 48, v13
	v_lshrrev_b32_e32 v24, 2, v13
	v_cmp_gt_i32_e64 s[38:39], s0, v13
	v_ashrrev_i32_e32 v32, 9, v13
	v_add_u32_e32 v33, 0x200, v13
	v_add_u32_e32 v34, 0x400, v13
	v_add_u32_e32 v35, 0x600, v13
	v_lshlrev_b32_e32 v13, 1, v13
	v_add_u32_e32 v11, 0, v10
	s_movk_i32 s1, 0x90
	v_ashrrev_i32_e32 v33, 9, v33
	v_ashrrev_i32_e32 v34, 9, v34
	v_ashrrev_i32_e32 v35, 9, v35
	v_and_b32_e32 v13, 0xffffff80, v13
	s_movk_i32 s0, 0x104
	v_and_b32_e32 v43, 1, v17
	v_lshlrev_b32_e32 v20, 4, v17
	v_lshlrev_b32_e32 v47, 4, v32
	v_lshl_or_b32 v32, v32, 6, v19
	v_lshlrev_b32_e32 v48, 4, v33
	v_lshl_or_b32 v33, v33, 6, v19
	v_lshlrev_b32_e32 v49, 4, v34
	v_lshl_or_b32 v34, v34, 6, v19
	v_lshlrev_b32_e32 v50, 4, v35
	v_lshl_or_b32 v19, v35, 6, v19
	v_add_u32_e32 v51, v11, v13
	v_add3_u32 v52, 0, v13, v10
	v_mul_lo_u32 v13, v17, s0
	v_mul_lo_u32 v35, v17, s1
	v_lshlrev_b32_e32 v17, 7, v17
	v_add_u32_e32 v36, 0x400, v17
	v_add_u32_e32 v53, v11, v36
	v_add3_u32 v54, 0, v36, v10
	v_add_u32_e32 v36, 0x800, v17
	v_and_b32_e32 v20, 48, v20
	v_add_u32_e32 v55, v11, v36
	v_add3_u32 v56, 0, v36, v10
	v_add_u32_e32 v36, 0xc00, v17
	v_or_b32_e32 v21, v20, v16
	v_add_u32_e32 v23, 0, v22
	v_add_u32_e32 v57, v11, v36
	v_add3_u32 v58, 0, v36, v10
	v_add_u32_e32 v36, 0x1000, v17
	v_mad_u32_u24 v44, v21, s1, v23
	v_lshl_or_b32 v21, v15, 7, v16
	v_and_or_b32 v20, v24, 12, v20
	v_lshlrev_b32_e32 v15, 12, v15
	v_add_u32_e32 v59, v11, v36
	v_add3_u32 v60, 0, v36, v10
	v_add_u32_e32 v36, 0x1400, v17
	v_add_u32_e32 v61, v11, v36
	v_add3_u32 v62, 0, v36, v10
	v_add_u32_e32 v36, 0x1800, v17
	v_add_u32_e32 v17, 0x1c00, v17
	v_lshl_or_b32 v15, v20, 6, v15
	v_add_u32_e32 v65, v11, v17
	v_add3_u32 v66, 0, v17, v10
	v_or_b32_e32 v17, v15, v16
	v_add_u32_e32 v14, v11, v10
	v_mul_lo_u32 v32, v32, s1
	v_mul_lo_u32 v33, v33, s1
	v_mul_lo_u32 v34, v34, s1
	v_mul_lo_u32 v19, v19, s1
	v_add3_u32 v64, 0, v36, v10
	v_mul_lo_u32 v10, v21, s1
	v_lshlrev_b32_e32 v17, 2, v17
	v_readlane_b32 s1, v254, 7
	v_readlane_b32 s0, v254, 6
	v_add3_u32 v68, 0, v10, v22
	v_add_u32_e32 v69, s1, v17
	v_add_u32_e32 v70, s0, v17
	v_or_b32_e32 v17, 64, v15
	v_or_b32_e32 v21, v17, v16
	v_lshlrev_b32_e32 v21, 2, v21
	v_add_u32_e32 v71, s1, v21
	v_add_u32_e32 v72, s0, v21
	v_or_b32_e32 v21, 0x80, v15
	v_or_b32_e32 v22, v21, v16
	v_lshlrev_b32_e32 v22, 2, v22
	v_add_u32_e32 v73, s1, v22
	v_add_u32_e32 v74, s0, v22
	v_or_b32_e32 v22, 0xc0, v15
	v_add_u32_e32 v67, v23, v10
	v_or_b32_e32 v23, v22, v16
	v_lshlrev_b32_e32 v23, 2, v23
	v_add_u32_e32 v75, s1, v23
	v_add_u32_e32 v76, s0, v23
	v_or_b32_e32 v23, 16, v16
	v_add_u32_e32 v63, v11, v36
	v_or_b32_e32 v36, v15, v23
	v_lshlrev_b32_e32 v36, 2, v36
	v_add_u32_e32 v77, s1, v36
	v_add_u32_e32 v78, s0, v36
	v_or_b32_e32 v36, v17, v23
	v_lshlrev_b32_e32 v36, 2, v36
	v_add_u32_e32 v79, s1, v36
	v_add_u32_e32 v80, s0, v36
	v_or_b32_e32 v36, v21, v23
	v_or_b32_e32 v23, v22, v23
	v_lshlrev_b32_e32 v23, 2, v23
	v_lshl_add_u32 v10, v16, 2, 0
	v_lshlrev_b32_e32 v36, 2, v36
	v_add_u32_e32 v83, s1, v23
	v_add_u32_e32 v84, s0, v23
	v_or_b32_e32 v23, 32, v16
	v_or_b32_e32 v16, 48, v16
	v_add_u32_e32 v81, s1, v36
	v_add_u32_e32 v82, s0, v36
	v_or_b32_e32 v36, v15, v23
	v_or_b32_e32 v15, v15, v16
	v_lshlrev_b32_e32 v15, 2, v15
	v_add_u32_e32 v93, s1, v15
	v_add_u32_e32 v94, s0, v15
	v_or_b32_e32 v15, v17, v16
	v_lshlrev_b32_e32 v15, 2, v15
	v_add_u32_e32 v95, s1, v15
	v_add_u32_e32 v96, s0, v15
	v_or_b32_e32 v15, v21, v16
	v_lshlrev_b32_e32 v15, 2, v15
	v_add_u32_e32 v97, s1, v15
	v_add_u32_e32 v98, s0, v15
	v_or_b32_e32 v15, v22, v16
	v_and_b32_e32 v24, -16, v12
	v_lshlrev_b32_e32 v15, 2, v15
	v_add_u32_e32 v99, s1, v15
	v_add_u32_e32 v100, s0, v15
	v_sub_u32_e32 v15, 63, v24
	v_cmp_eq_u32_e32 vcc, 0, v43
	v_lshl_or_b32 v25, v43, 12, v26
	v_lshl_add_u32 v29, v12, 7, v18
	v_cndmask_b32_e32 v15, v15, v24, vcc
	v_lshlrev_b32_e32 v15, 6, v15
	v_add_lshl_u32 v15, v15, v25, 2
	v_add_u32_e32 v101, s1, v15
	v_add_u32_e32 v102, s0, v15
; __device__ __forceinline__ int lbid() { int b = blockIdx.x; asm volatile("" : "+s"(b)); return b; }
; template <int PASS>
; __device__ void lru_items(const Params& p, unsigned char* shm, int l) {
;     ...
;     int n_loaded = -1;
;     float c0 = 0.f, c1 = 0.f, c2 = 0.f, c3 = 0.f, cb = 0.f, gba[4], gbx[4], gsp[4];
; #pragma unroll
;     for (int jt = 0; jt < 4; ++jt) { gba[jt] = 0.f; gbx[jt] = 0.f; gsp[jt] = 0.f; }
;     u32x4 xr0 = (u32x4){0u, 0u, 0u, 0u}, xr1 = (u32x4){0u, 0u, 0u, 0u};
;     ...
;     int it = lbid();
;     if (it < total) LRU_LOAD(it);
;     ...
;         {
;             const int seg = tid >> 7, d = (tid >> 6) & 1, j = tid & 63;
;             float h = 0.f, P = 1.f;
; #pragma unroll
;             for (int s = 0; s < 16; ++s) { const int st = seg * 16 + s, t = d ? 63 - st : st; const float a = As[(d * 64 + t) * 64 + j]; h = a * h + Bs[(d * 64 + t) * 64 + j]; P *= a; }
;             Pq[seg * 128 + (tid & 127)] = P; Hq[seg * 128 + (tid & 127)] = h;
;             __syncthreads();
;             if (PASS == 0) {
;                 if (tid < 128) { float hh = Hq[tid], PP = Pq[tid];
; #pragma unroll
;                     for (int q = 1; q < 4; ++q) { const float pq = Pq[q * 128 + tid]; hh = pq * hh + Hq[q * 128 + tid]; PP *= pq; }
;                     SA[so] = PP; SH[so] = hh; }
	v_or_b32_e32 v15, 1, v24
	v_sub_u32_e32 v16, 63, v15
	v_cndmask_b32_e32 v15, v16, v15, vcc
	v_lshlrev_b32_e32 v15, 6, v15
	v_add_lshl_u32 v15, v15, v25, 2
	v_add_u32_e32 v103, s1, v15
	v_add_u32_e32 v104, s0, v15
	v_or_b32_e32 v15, 2, v24
	v_sub_u32_e32 v16, 63, v15
	v_cndmask_b32_e32 v15, v16, v15, vcc
	v_lshlrev_b32_e32 v15, 6, v15
	v_add_lshl_u32 v15, v15, v25, 2
	v_add_u32_e32 v105, s1, v15
	v_add_u32_e32 v106, s0, v15
	v_or_b32_e32 v15, 3, v24
	v_sub_u32_e32 v16, 63, v15
	v_cndmask_b32_e32 v15, v16, v15, vcc
	v_lshlrev_b32_e32 v15, 6, v15
	v_add_lshl_u32 v15, v15, v25, 2
	v_add_u32_e32 v107, s1, v15
	v_add_u32_e32 v108, s0, v15
	v_or_b32_e32 v15, 4, v24
	v_sub_u32_e32 v16, 63, v15
	v_cndmask_b32_e32 v15, v16, v15, vcc
	v_lshlrev_b32_e32 v15, 6, v15
	v_add_lshl_u32 v15, v15, v25, 2
	v_add_u32_e32 v109, s1, v15
	v_add_u32_e32 v110, s0, v15
	v_or_b32_e32 v15, 5, v24
	v_sub_u32_e32 v16, 63, v15
	v_cndmask_b32_e32 v15, v16, v15, vcc
	v_lshlrev_b32_e32 v15, 6, v15
	v_add_lshl_u32 v15, v15, v25, 2
	v_add_u32_e32 v111, s1, v15
	v_add_u32_e32 v112, s0, v15
	v_or_b32_e32 v15, 6, v24
	v_sub_u32_e32 v16, 63, v15
	v_cndmask_b32_e32 v15, v16, v15, vcc
	v_lshlrev_b32_e32 v15, 6, v15
	v_add_lshl_u32 v15, v15, v25, 2
	v_add_u32_e32 v113, s1, v15
	v_add_u32_e32 v114, s0, v15
	v_or_b32_e32 v15, 7, v24
	v_sub_u32_e32 v16, 63, v15
	v_cndmask_b32_e32 v15, v16, v15, vcc
	v_lshlrev_b32_e32 v15, 6, v15
	v_add_lshl_u32 v15, v15, v25, 2
	v_add_u32_e32 v115, s1, v15
	v_add_u32_e32 v116, s0, v15
	v_or_b32_e32 v15, 8, v24
	v_sub_u32_e32 v16, 63, v15
	v_cndmask_b32_e32 v15, v16, v15, vcc
	v_lshlrev_b32_e32 v15, 6, v15
	v_add_lshl_u32 v15, v15, v25, 2
	v_add_u32_e32 v117, s1, v15
	v_add_u32_e32 v118, s0, v15
	v_or_b32_e32 v15, 9, v24
	v_sub_u32_e32 v16, 63, v15
	v_cndmask_b32_e32 v15, v16, v15, vcc
	v_lshlrev_b32_e32 v15, 6, v15
	v_add_lshl_u32 v15, v15, v25, 2
	v_add_u32_e32 v119, s1, v15
	v_add_u32_e32 v120, s0, v15
	v_or_b32_e32 v15, 10, v24
	v_sub_u32_e32 v16, 63, v15
	v_cndmask_b32_e32 v15, v16, v15, vcc
	v_lshlrev_b32_e32 v15, 6, v15
	v_add_lshl_u32 v15, v15, v25, 2
	v_add_u32_e32 v121, s1, v15
	v_add_u32_e32 v122, s0, v15
	v_or_b32_e32 v15, 11, v24
	v_sub_u32_e32 v16, 63, v15
	v_cndmask_b32_e32 v15, v16, v15, vcc
	v_lshlrev_b32_e32 v15, 6, v15
	v_add_lshl_u32 v15, v15, v25, 2
	v_add_u32_e32 v123, s1, v15
	v_add_u32_e32 v124, s0, v15
	v_or_b32_e32 v15, 12, v24
	v_sub_u32_e32 v16, 63, v15
	v_cndmask_b32_e32 v15, v16, v15, vcc
	v_lshlrev_b32_e32 v15, 6, v15
	v_add_lshl_u32 v15, v15, v25, 2
	v_add_u32_e32 v125, s1, v15
	v_add_u32_e32 v126, s0, v15
	v_or_b32_e32 v15, 13, v24
	v_sub_u32_e32 v16, 63, v15
	v_cndmask_b32_e32 v15, v16, v15, vcc
	v_lshlrev_b32_e32 v15, 6, v15
	v_add_lshl_u32 v15, v15, v25, 2
	v_add_u32_e32 v127, s1, v15
	v_add_u32_e32 v128, s0, v15
	v_or_b32_e32 v15, 14, v24
	v_sub_u32_e32 v16, 63, v15
	v_cndmask_b32_e32 v15, v16, v15, vcc
	v_lshlrev_b32_e32 v15, 6, v15
	v_add_lshl_u32 v15, v15, v25, 2
	v_or_b32_e32 v12, 15, v12
	v_lshlrev_b32_e32 v36, 2, v36
	v_add_u32_e32 v129, s1, v15
	v_add_u32_e32 v131, s0, v15
	v_sub_u32_e32 v15, 63, v12
	v_add_u32_e32 v85, s1, v36
	v_add_u32_e32 v86, s0, v36
	v_or_b32_e32 v36, v17, v23
	v_cndmask_b32_e32 v12, v15, v12, vcc
	v_lshlrev_b32_e32 v36, 2, v36
	v_lshlrev_b32_e32 v12, 6, v12
	v_add_u32_e32 v87, s1, v36
	v_add_u32_e32 v88, s0, v36
	v_or_b32_e32 v36, v21, v23
	v_or_b32_e32 v23, v22, v23
	v_add_lshl_u32 v12, v12, v25, 2
	v_readlane_b32 s3, v254, 4
	v_readlane_b32 s4, v254, 5
	v_lshlrev_b32_e32 v36, 2, v36
	v_lshlrev_b32_e32 v23, 2, v23
	v_add_u32_e32 v132, s1, v12
	v_add_u32_e32 v133, s0, v12
	v_add_u32_e32 v12, 0x200, v0
	v_add_u32_e32 v45, s3, v0
	v_add_u32_e32 v46, s4, v0
	v_add_u32_e32 v89, s1, v36
	v_add_u32_e32 v90, s0, v36
	v_add_u32_e32 v91, s1, v23
	v_add_u32_e32 v92, s0, v23
	v_add_u32_e32 v134, s3, v12
	v_add_u32_e32 v135, s4, v12
	v_add_u32_e32 v12, 0x400, v0
	v_add_u32_e32 v0, 0x600, v0
	v_readlane_b32 s0, v251, 10
	v_mul_u32_u24_e32 v20, 0x104, v20
	v_add_u32_e32 v138, s3, v0
	v_add_u32_e32 v139, s4, v0
	s_add_i32 s0, s0, s2
	v_mov_b32_e32 v0, v1
	v_add_u32_e32 v136, s3, v12
	v_add_u32_e32 v137, s4, v12
	s_lshl_b32 s3, s0, 2
	s_mov_b32 s6, -1
	v_add_u32_e32 v141, v18, v32
	v_add_u32_e32 v142, v18, v33
	v_add_u32_e32 v143, v18, v34
	v_add_u32_e32 v144, v18, v19
	v_add_u32_e32 v145, v14, v13
	v_add_u32_e32 v146, v11, v35
	v_add_u32_e32 v147, v10, v20
	v_mov_b32_e32 v154, 0
	v_mov_b32_e32 v155, 0
	v_mov_b32_e32 v156, 0
	v_mov_b32_e32 v157, 0
	v_mov_b64_e32 v[32:33], v[0:1]
	v_mov_b64_e32 v[34:35], v[0:1]
	v_mov_b32_e32 v158, 0
	v_mov_b32_e32 v159, 0
	v_mov_b32_e32 v160, 0
	v_mov_b32_e32 v161, 0
	v_mov_b32_e32 v162, 0
	v_mov_b32_e32 v163, 0
	v_mov_b32_e32 v164, 0
	v_mov_b32_e32 v165, 0
	v_readlane_b32 s61, v251, 21
	v_readlane_b32 s62, v251, 22
	v_readlane_b32 s63, v251, 23
	v_readlane_b32 s64, v251, 24
	v_readlane_b32 s65, v251, 25
	v_readlane_b32 s66, v251, 26
	v_readlane_b32 s67, v251, 27
	v_readlane_b32 s72, v251, 32
	v_readlane_b32 s73, v251, 33
	v_readlane_b32 s74, v251, 34
	v_readlane_b32 s75, v251, 35
	v_readlane_b32 s1, v251, 11
	s_waitcnt vmcnt(0)
	s_branch .LBB0_296

; template <int PASS>
; __device__ void lru_items(const Params& p, unsigned char* shm, int l) {
;     ...
;     for (; it < total; it += G_) {
;         const int ck = it >> 4, n = it & 15, t0 = ck * 64;
;         *(u32x4*)(xraw + (tid >> 3) * 64 + (tid & 7) * 8) = xr0;
;         if (tid < 24) *(u32x4*)(xraw + (64 + (tid >> 3)) * 64 + (tid & 7) * 8) = xr1;
;         if (n != n_loaded) {
;             n_loaded = n;
; #pragma unroll
;             for (int i = 0; i < 4; ++i) { const int e = tid + 512 * i, mtx = e >> 9, rem = e & 511, j = rem >> 3, c8 = rem & 7;
;                 *(u32x4*)(wt + (mtx * 64 + j) * 72 + c8 * 8) = *(const u32x4*)(LWT + ((size_t)(mtx * 16 + n) * 64 + j) * 64 + c8 * 8); }
;             { const int ch = n * 64 + (tid & 63); c0 = cw[ch]; c1 = cw[1024 + ch]; c2 = cw[2048 + ch]; c3 = cw[3072 + ch]; cb = cbias[ch]; }
; #pragma unroll
;             for (int jt = 0; jt < 4; ++jt) { const int pi = (l * 2 + (w >> 2)) * 1024 + n * 64 + jt * 16 + fr; gba[jt] = p.in[7][pi]; gbx[jt] = p.in[9][pi]; gsp[jt] = -8.0f * log1pf(__expf(-p.in[10][pi])); }
;     ...
;             if (PASS == 0) {
;                 if (tid < 128) { float hh = Hq[tid], PP = Pq[tid];
; #pragma unroll
;                     for (int q = 1; q < 4; ++q) { const float pq = Pq[q * 128 + tid]; hh = pq * hh + Hq[q * 128 + tid]; PP *= pq; }
;                     SA[so] = PP; SH[so] = hh; }
.LBB0_296:
	s_cmp_lg_u64 s[38:39], 0
	s_cbranch_scc1 .Llru0_w01
	s_waitcnt vmcnt(0)
	s_branch .Llru0_wj
.Llru0_w01:
	s_waitcnt vmcnt(2)
.Llru0_wj:
	ds_write_b128 v29, v[2:5]
	s_and_saveexec_b64 s[0:1], s[36:37]
	ds_write_b128 v29, v[6:9] offset:8192
	s_or_b64 exec, exec, s[0:1]
	s_and_b32 s4, s2, 15
	s_cmp_lg_u32 s4, s6
	s_mov_b64 s[0:1], -1
	s_cbranch_scc0 .LBB0_300
	v_or_b32_e32 v10, s4, v47
	v_or_b32_e32 v12, s4, v48
	s_lshl_b32 s50, s4, 6
	v_ashrrev_i32_e32 v11, 31, v10
	v_ashrrev_i32_e32 v13, 31, v12
	v_or_b32_e32 v22, s50, v42
	v_lshlrev_b64 v[10:11], 13, v[10:11]
	v_lshlrev_b64 v[12:13], 13, v[12:13]
	v_ashrrev_i32_e32 v23, 31, v22
	v_readlane_b32 s76, v251, 36
	v_lshl_add_u64 v[10:11], v[30:31], 0, v[10:11]
	v_lshl_add_u64 v[14:15], v[30:31], 0, v[12:13]
	v_lshlrev_b64 v[36:37], 2, v[22:23]
	v_readlane_b32 s80, v251, 40
	v_readlane_b32 s81, v251, 41
	global_load_dwordx4 v[10:13], v[10:11], off
	s_nop 0
	global_load_dwordx4 v[14:17], v[14:15], off
	v_lshl_add_u64 v[40:41], s[80:81], 0, v[36:37]
	global_load_dword v168, v[40:41], off
	global_load_dword v169, v[40:41], off offset:64
	v_or_b32_e32 v18, s4, v49
	v_or_b32_e32 v20, s4, v50
	v_ashrrev_i32_e32 v19, 31, v18
	v_ashrrev_i32_e32 v21, 31, v20
	v_lshlrev_b64 v[18:19], 13, v[18:19]
	v_lshlrev_b64 v[20:21], 13, v[20:21]
	v_lshl_add_u64 v[18:19], v[30:31], 0, v[18:19]
	v_lshl_add_u64 v[22:23], v[30:31], 0, v[20:21]
	global_load_dwordx4 v[18:21], v[18:19], off
	s_nop 0
	global_load_dwordx4 v[22:25], v[22:23], off
	v_or_b32_e32 v0, s50, v26
	v_lshlrev_b32_e32 v0, 2, v0
	v_lshl_add_u64 v[38:39], s[42:43], 0, v[0:1]
	s_movk_i32 s0, 0x2000
	v_add_co_u32_e32 v150, vcc, s0, v38
	s_movk_i32 s0, 0x3000
	s_nop 0
	v_addc_co_u32_e32 v151, vcc, 0, v39, vcc
	v_add_co_u32_e32 v166, vcc, s0, v38
	global_load_dword v149, v0, s[42:43]
	global_load_dword v148, v0, s[46:47]
	v_addc_co_u32_e32 v167, vcc, 0, v39, vcc
	global_load_dword v152, v[150:151], off offset:-4096
	s_nop 0
	global_load_dword v151, v[150:151], off
	s_nop 0
	global_load_dword v150, v[166:167], off
	global_load_dword v0, v[40:41], off offset:128
	global_load_dword v176, v[40:41], off offset:192
	s_mov_b32 s0, 0x3f2aaaab
	s_mov_b32 s8, 0x3ecc95a3
	s_mov_b32 s18, 0x3f2aaada
	s_mov_b32 s28, 0x3f317218
	s_mov_b32 s40, 0xb102e308
	s_mov_b32 s1, 0x7f800000
	s_mov_b32 s5, 0x33800000
	s_mov_b32 s48, 0xc1000000
	v_readlane_b32 s60, v251, 20
	v_readlane_b32 s78, v251, 38
	v_readlane_b32 s79, v251, 39
	v_readlane_b32 s74, v251, 34
	v_readlane_b32 s75, v251, 35
	v_readlane_b32 s88, v251, 48
	v_readlane_b32 s89, v251, 49
	v_lshl_add_u64 v[38:39], s[74:75], 0, v[36:37]
	v_lshl_add_u64 v[36:37], s[78:79], 0, v[36:37]
	v_readlane_b32 s90, v251, 50
	v_readlane_b32 s91, v251, 51
	v_readlane_b32 s82, v251, 42
	v_readlane_b32 s84, v251, 44
	v_readlane_b32 s88, v254, 27
	v_readlane_b32 s90, v254, 25
	v_readlane_b32 s77, v251, 37
	v_readlane_b32 s83, v251, 43
	v_readlane_b32 s85, v251, 45
	v_readlane_b32 s86, v251, 46
	v_readlane_b32 s87, v251, 47
	v_readlane_b32 s92, v254, 21
	v_readlane_b32 s84, v254, 58
	s_movk_i32 s82, 0x60
	v_readlane_b32 s89, v254, 28
	v_readlane_b32 s91, v254, 26
	v_readlane_b32 s80, v254, 20
	v_readlane_b32 s61, v251, 21
	v_readlane_b32 s62, v251, 22
	v_readlane_b32 s63, v251, 23
	v_readlane_b32 s64, v251, 24
	v_readlane_b32 s65, v251, 25
	v_readlane_b32 s66, v251, 26
	v_readlane_b32 s67, v251, 27
	v_readlane_b32 s68, v251, 28
	s_waitcnt vmcnt(12)
	ds_write_b128 v141, v[10:13] offset:34560
	s_waitcnt vmcnt(11)
	ds_write_b128 v142, v[14:17] offset:34560
	s_waitcnt vmcnt(10)
	v_mul_f32_e32 v10, 0xbfb8aa3b, v168
	v_exp_f32_e32 v177, v10
	s_waitcnt vmcnt(9)
	v_mul_f32_e32 v11, 0xbfb8aa3b, v169
	v_exp_f32_e32 v178, v11
	s_waitcnt vmcnt(8)
	ds_write_b128 v143, v[18:21] offset:34560
	s_waitcnt vmcnt(7)
	ds_write_b128 v144, v[22:25] offset:34560
	v_add_f32_e32 v14, 1.0, v177
	v_frexp_mant_f32_e32 v17, v14
	v_cvt_f64_f32_e32 v[10:11], v14
	v_add_f32_e32 v15, 1.0, v178
	v_frexp_exp_i32_f64_e32 v10, v[10:11]
	v_cmp_gt_f32_e32 vcc, s0, v17
	v_add_f32_e32 v16, -1.0, v14
	v_frexp_mant_f32_e32 v19, v15
	v_cvt_f64_f32_e32 v[12:13], v15
	v_subbrev_co_u32_e32 v168, vcc, 0, v10, vcc
	v_add_f32_e32 v18, -1.0, v15
	v_sub_f32_e32 v20, v16, v14
	v_frexp_exp_i32_f64_e32 v12, v[12:13]
	v_cmp_gt_f32_e32 vcc, s0, v19
	v_sub_f32_e32 v16, v177, v16
	v_sub_f32_e32 v11, v18, v15
	v_add_f32_e32 v13, 1.0, v20
	v_subbrev_co_u32_e32 v169, vcc, 0, v12, vcc
	v_sub_f32_e32 v18, v178, v18
	v_add_f32_e32 v10, 1.0, v11
	v_add_f32_e32 v12, v16, v13
	v_sub_u32_e32 v13, 0, v168
	v_sub_u32_e32 v17, 0, v169
	v_add_f32_e32 v16, v18, v10
	v_ldexp_f32 v11, v14, v13
	v_ldexp_f32 v10, v15, v17
	v_pk_add_f32 v[14:15], v[10:11], 1.0 op_sel_hi:[1,0]
	v_ldexp_f32 v13, v12, v13
	v_ldexp_f32 v12, v16, v17
	v_pk_add_f32 v[16:17], v[10:11], -1.0 op_sel_hi:[1,0]
	v_pk_add_f32 v[18:19], v[14:15], -1.0 op_sel_hi:[1,0]
	v_pk_add_f32 v[20:21], v[16:17], 1.0 op_sel_hi:[1,0]
	v_pk_add_f32 v[18:19], v[10:11], v[18:19] neg_lo:[0,1] neg_hi:[0,1]
	v_pk_add_f32 v[10:11], v[10:11], v[20:21] neg_lo:[0,1] neg_hi:[0,1]
	v_pk_add_f32 v[18:19], v[12:13], v[18:19]
	v_pk_add_f32 v[10:11], v[12:13], v[10:11]
	v_pk_add_f32 v[12:13], v[14:15], v[18:19]
	v_pk_add_f32 v[20:21], v[16:17], v[10:11]
	v_rcp_f32_e32 v23, v13
	v_rcp_f32_e32 v22, v12
	v_pk_add_f32 v[16:17], v[20:21], v[16:17] neg_lo:[0,1] neg_hi:[0,1]
	v_pk_add_f32 v[14:15], v[12:13], v[14:15] neg_lo:[0,1] neg_hi:[0,1]
	v_pk_add_f32 v[10:11], v[10:11], v[16:17] neg_lo:[0,1] neg_hi:[0,1]
	v_pk_mul_f32 v[16:17], v[20:21], v[22:23]
	v_pk_add_f32 v[14:15], v[18:19], v[14:15] neg_lo:[0,1] neg_hi:[0,1]
	v_pk_mul_f32 v[18:19], v[12:13], v[16:17]
	v_cmp_neq_f32_e32 vcc, s1, v178
	v_pk_fma_f32 v[24:25], v[16:17], v[12:13], v[18:19] neg_lo:[0,0,1] neg_hi:[0,0,1]
	s_waitcnt vmcnt(1)
; template <int PASS>
; __device__ void lru_items(const Params& p, unsigned char* shm, int l) {
;     ...
;             { const int ch = n * 64 + (tid & 63); c0 = cw[ch]; c1 = cw[1024 + ch]; c2 = cw[2048 + ch]; c3 = cw[3072 + ch]; cb = cbias[ch]; }
; #pragma unroll
;             for (int jt = 0; jt < 4; ++jt) { const int pi = (l * 2 + (w >> 2)) * 1024 + n * 64 + jt * 16 + fr; gba[jt] = p.in[7][pi]; gbx[jt] = p.in[9][pi]; gsp[jt] = -8.0f * log1pf(__expf(-p.in[10][pi])); }
	v_mul_f32_e32 v0, 0xbfb8aa3b, v0
	v_pk_fma_f32 v[24:25], v[16:17], v[14:15], v[24:25]
	v_exp_f32_e32 v0, v0
	v_pk_add_f32 v[40:41], v[18:19], v[24:25]
	v_readlane_b32 s69, v251, 29
	v_pk_add_f32 v[166:167], v[20:21], v[40:41] neg_lo:[0,1] neg_hi:[0,1]
	v_pk_add_f32 v[18:19], v[40:41], v[18:19] neg_lo:[0,1] neg_hi:[0,1]
	v_pk_add_f32 v[20:21], v[20:21], v[166:167] neg_lo:[0,1] neg_hi:[0,1]
	v_pk_add_f32 v[18:19], v[18:19], v[24:25] neg_lo:[0,1] neg_hi:[0,1]
	v_pk_add_f32 v[20:21], v[20:21], v[40:41] neg_lo:[0,1] neg_hi:[0,1]
	v_readlane_b32 s70, v251, 30
	v_pk_add_f32 v[10:11], v[10:11], v[20:21]
	v_readlane_b32 s71, v251, 31
	v_pk_add_f32 v[10:11], v[18:19], v[10:11]
	v_readlane_b32 s72, v251, 32
	v_pk_add_f32 v[18:19], v[166:167], v[10:11]
	v_readlane_b32 s73, v251, 33
	v_pk_mul_f32 v[20:21], v[22:23], v[18:19]
	v_pk_add_f32 v[24:25], v[166:167], v[18:19] neg_lo:[0,1] neg_hi:[0,1]
	v_pk_mul_f32 v[40:41], v[12:13], v[20:21]
	v_pk_add_f32 v[10:11], v[10:11], v[24:25]
	v_pk_fma_f32 v[12:13], v[20:21], v[12:13], v[40:41] neg_lo:[0,0,1] neg_hi:[0,0,1]
	s_nop 0
	v_pk_fma_f32 v[12:13], v[20:21], v[14:15], v[12:13]
	s_nop 0
	v_pk_add_f32 v[14:15], v[40:41], v[12:13]
	s_nop 0
	v_pk_add_f32 v[24:25], v[14:15], v[40:41] neg_lo:[0,1] neg_hi:[0,1]
	v_pk_add_f32 v[40:41], v[18:19], v[14:15] neg_lo:[0,1] neg_hi:[0,1]
	v_pk_add_f32 v[12:13], v[24:25], v[12:13] neg_lo:[0,1] neg_hi:[0,1]
	v_pk_add_f32 v[18:19], v[18:19], v[40:41] neg_lo:[0,1] neg_hi:[0,1]
	s_nop 0
	v_pk_add_f32 v[14:15], v[18:19], v[14:15] neg_lo:[0,1] neg_hi:[0,1]
	s_nop 0
	v_pk_add_f32 v[10:11], v[10:11], v[14:15]
	s_nop 0
	v_pk_add_f32 v[10:11], v[12:13], v[10:11]
	v_pk_add_f32 v[12:13], v[16:17], v[20:21]
	v_pk_add_f32 v[10:11], v[40:41], v[10:11]
	v_pk_add_f32 v[14:15], v[12:13], v[16:17] neg_lo:[0,1] neg_hi:[0,1]
	v_pk_mul_f32 v[10:11], v[22:23], v[10:11]
	v_pk_add_f32 v[14:15], v[20:21], v[14:15] neg_lo:[0,1] neg_hi:[0,1]
	v_mov_b64_e32 v[20:21], s[8:9]
	v_pk_add_f32 v[10:11], v[14:15], v[10:11]
	s_mov_b32 s8, 0x3e9b6dac
	v_pk_add_f32 v[14:15], v[12:13], v[10:11]
	v_cvt_f32_i32_e32 v23, v168
	v_pk_mul_f32 v[16:17], v[14:15], v[14:15]
	v_cvt_f32_i32_e32 v22, v169
	v_pk_add_f32 v[12:13], v[14:15], v[12:13] neg_lo:[0,1] neg_hi:[0,1]
	v_pk_fma_f32 v[18:19], v[16:17], s[8:9], v[20:21] op_sel_hi:[1,0,0]
	v_pk_add_f32 v[10:11], v[10:11], v[12:13] neg_lo:[0,1] neg_hi:[0,1]
	v_ldexp_f32 v13, v15, 1
	v_pk_fma_f32 v[18:19], v[16:17], v[18:19], s[18:19] op_sel_hi:[1,1,0]
	v_ldexp_f32 v12, v14, 1
	v_pk_mul_f32 v[14:15], v[14:15], v[16:17]
	v_pk_mul_f32 v[16:17], v[22:23], s[28:29] op_sel_hi:[1,0]
	v_pk_mul_f32 v[14:15], v[14:15], v[18:19]
	v_pk_fma_f32 v[40:41], v[22:23], s[28:29], v[16:17] op_sel_hi:[1,0,1] neg_lo:[0,0,1] neg_hi:[0,0,1]
	v_pk_add_f32 v[18:19], v[12:13], v[14:15]
	v_ldexp_f32 v11, v11, 1
	v_pk_add_f32 v[12:13], v[18:19], v[12:13] neg_lo:[0,1] neg_hi:[0,1]
	v_pk_fma_f32 v[22:23], v[22:23], s[40:41], v[40:41] op_sel_hi:[1,0,1]
	v_pk_add_f32 v[12:13], v[14:15], v[12:13] neg_lo:[0,1] neg_hi:[0,1]
	v_ldexp_f32 v24, v10, 1
	v_mov_b32_e32 v14, v16
	v_mov_b32_e32 v15, v13
	v_mov_b32_e32 v10, v22
	v_mov_b32_e32 v25, v11
	v_pk_add_f32 v[14:15], v[14:15], v[10:11]
	v_pk_add_f32 v[10:11], v[24:25], v[12:13]
	v_mov_b32_e32 v13, v19
	v_mov_b32_e32 v25, v11
	v_pk_add_f32 v[40:41], v[16:17], v[22:23]
	v_pk_add_f32 v[12:13], v[24:25], v[12:13]
	v_pk_add_f32 v[24:25], v[18:19], v[10:11]
	v_mov_b32_e32 v170, v18
	v_pk_add_f32 v[166:167], v[40:41], v[24:25]
	v_mov_b32_e32 v168, v24
	v_mov_b32_e32 v169, v167
	v_mov_b32_e32 v171, v41
	v_pk_add_f32 v[168:169], v[168:169], v[170:171] neg_lo:[0,1] neg_hi:[0,1]
	v_mov_b32_e32 v170, v40
	v_mov_b32_e32 v171, v167
	v_mov_b32_e32 v172, v16
	v_mov_b32_e32 v173, v169
	v_pk_add_f32 v[170:171], v[170:171], v[172:173] neg_lo:[0,1] neg_hi:[0,1]
	v_mov_b32_e32 v173, v41
	v_mov_b32_e32 v174, v166
	v_mov_b32_e32 v175, v41
	v_mov_b32_e32 v41, v17
	v_mov_b32_e32 v172, v22
	v_pk_add_f32 v[16:17], v[174:175], v[40:41] neg_lo:[0,1] neg_hi:[0,1]
	v_pk_add_f32 v[172:173], v[172:173], v[170:171] neg_lo:[0,1] neg_hi:[0,1]
	v_mov_b32_e32 v171, v17
	v_pk_add_f32 v[40:41], v[22:23], v[170:171] neg_lo:[0,1] neg_hi:[0,1]
	v_pk_add_f32 v[170:171], v[24:25], v[18:19] neg_lo:[0,1] neg_hi:[0,1]
	v_pk_add_f32 v[12:13], v[12:13], v[168:169] neg_lo:[0,1] neg_hi:[0,1]
	v_mov_b32_e32 v168, v166
	v_mov_b32_e32 v169, v25
	v_mov_b32_e32 v18, v16
	v_pk_add_f32 v[18:19], v[168:169], v[18:19] neg_lo:[0,1] neg_hi:[0,1]
	v_mov_b32_e32 v25, v23
	v_pk_add_f32 v[14:15], v[14:15], v[18:19] neg_lo:[0,1] neg_hi:[0,1]
	v_pk_add_f32 v[16:17], v[24:25], v[16:17] neg_lo:[0,1] neg_hi:[0,1]
	v_pk_add_f32 v[22:23], v[12:13], v[172:173]
	v_mov_b32_e32 v173, v17
	v_mov_b32_e32 v13, v15
	v_pk_add_f32 v[18:19], v[16:17], v[14:15]
	v_pk_add_f32 v[12:13], v[172:173], v[12:13]
	v_mov_b32_e32 v14, v22
	v_pk_add_f32 v[12:13], v[12:13], v[40:41] neg_lo:[0,1] neg_hi:[0,1]
	v_mov_b32_e32 v15, v19
	v_pk_add_f32 v[10:11], v[10:11], v[170:171] neg_lo:[0,1] neg_hi:[0,1]
	v_pk_add_f32 v[14:15], v[14:15], v[12:13] neg_lo:[0,1] neg_hi:[0,1]
	v_pk_add_f32 v[10:11], v[10:11], v[12:13] neg_lo:[0,1] neg_hi:[0,1]
	v_pk_add_f32 v[14:15], v[172:173], v[14:15] neg_lo:[0,1] neg_hi:[0,1]
	v_pk_add_f32 v[12:13], v[18:19], v[22:23]
	v_pk_add_f32 v[10:11], v[10:11], v[14:15]
	v_pk_add_f32 v[14:15], v[166:167], v[12:13]
	global_load_dword v22, v[38:39], off
	global_load_dword v23, v[38:39], off offset:64
	global_load_dword v24, v[38:39], off offset:128
	global_load_dword v25, v[38:39], off offset:192
	v_pk_add_f32 v[16:17], v[14:15], v[166:167] neg_lo:[0,1] neg_hi:[0,1]
	global_load_dword v38, v[36:37], off
	global_load_dword v39, v[36:37], off offset:64
; template <int PASS>
; __device__ void lru_items(const Params& p, unsigned char* shm, int l) {
;     ...
;             { const int ch = n * 64 + (tid & 63); c0 = cw[ch]; c1 = cw[1024 + ch]; c2 = cw[2048 + ch]; c3 = cw[3072 + ch]; cb = cbias[ch]; }
; #pragma unroll
;             for (int jt = 0; jt < 4; ++jt) { const int pi = (l * 2 + (w >> 2)) * 1024 + n * 64 + jt * 16 + fr; gba[jt] = p.in[7][pi]; gbx[jt] = p.in[9][pi]; gsp[jt] = -8.0f * log1pf(__expf(-p.in[10][pi])); }
	global_load_dword v40, v[36:37], off offset:128
	s_nop 0
	global_load_dword v36, v[36:37], off offset:192
	v_pk_add_f32 v[12:13], v[12:13], v[16:17] neg_lo:[0,1] neg_hi:[0,1]
	s_nop 0
	v_pk_add_f32 v[10:11], v[10:11], v[12:13]
	v_add_f32_e32 v12, 1.0, v0
	v_pk_add_f32 v[10:11], v[14:15], v[10:11]
	v_frexp_mant_f32_e32 v14, v12
	v_cndmask_b32_e32 v10, v237, v10, vcc
	v_cmp_neq_f32_e32 vcc, s1, v177
	s_nop 1
	v_cndmask_b32_e32 v11, v237, v11, vcc
	v_cmp_ngt_f32_e32 vcc, -1.0, v177
	s_nop 1
	v_cndmask_b32_e32 v11, v238, v11, vcc
	v_cmp_ngt_f32_e32 vcc, -1.0, v178
	s_nop 1
	v_cndmask_b32_e32 v10, v238, v10, vcc
	v_cmp_neq_f32_e32 vcc, -1.0, v178
	s_nop 1
	v_cndmask_b32_e32 v10, v239, v10, vcc
	v_cmp_neq_f32_e32 vcc, -1.0, v177
	s_nop 1
	v_cndmask_b32_e32 v11, v239, v11, vcc
	v_cmp_lt_f32_e64 vcc, |v177|, s5
	s_nop 1
	v_cndmask_b32_e32 v11, v11, v177, vcc
	v_cmp_lt_f32_e64 vcc, |v178|, s5
	s_nop 1
	v_cndmask_b32_e32 v10, v10, v178, vcc
	v_pk_mul_f32 v[18:19], v[10:11], s[48:49] op_sel_hi:[1,0]
	v_add_f32_e32 v10, -1.0, v12
	v_sub_f32_e32 v11, v10, v12
	v_add_f32_e32 v11, 1.0, v11
	v_sub_f32_e32 v10, v0, v10
	v_add_f32_e32 v13, v10, v11
	v_cvt_f64_f32_e32 v[10:11], v12
	v_frexp_exp_i32_f64_e32 v10, v[10:11]
	v_cmp_gt_f32_e32 vcc, s0, v14
	s_nop 1
	v_subbrev_co_u32_e32 v41, vcc, 0, v10, vcc
	v_sub_u32_e32 v10, 0, v41
	v_ldexp_f32 v11, v12, v10
	v_ldexp_f32 v13, v13, v10
	s_waitcnt vmcnt(8)
	v_mul_f32_e32 v10, 0xbfb8aa3b, v176
	v_exp_f32_e32 v182, v10
	s_nop 0
	v_add_f32_e32 v10, 1.0, v182
	v_add_f32_e32 v12, -1.0, v10
	v_sub_f32_e32 v14, v12, v10
	v_add_f32_e32 v14, 1.0, v14
	v_sub_f32_e32 v12, v182, v12
	v_add_f32_e32 v12, v12, v14
	v_frexp_mant_f32_e32 v16, v10
	v_cvt_f64_f32_e32 v[14:15], v10
	v_frexp_exp_i32_f64_e32 v14, v[14:15]
	v_cmp_gt_f32_e32 vcc, s0, v16
	s_nop 1
	v_subbrev_co_u32_e32 v37, vcc, 0, v14, vcc
	v_sub_u32_e32 v14, 0, v37
	v_ldexp_f32 v10, v10, v14
	v_ldexp_f32 v12, v12, v14
	v_pk_add_f32 v[14:15], v[10:11], 1.0 op_sel_hi:[1,0]
	v_pk_add_f32 v[170:171], v[10:11], -1.0 op_sel_hi:[1,0]
	v_pk_add_f32 v[16:17], v[14:15], -1.0 op_sel_hi:[1,0]
	v_pk_add_f32 v[172:173], v[170:171], 1.0 op_sel_hi:[1,0]
	v_pk_add_f32 v[16:17], v[10:11], v[16:17] neg_lo:[0,1] neg_hi:[0,1]
	v_pk_add_f32 v[10:11], v[10:11], v[172:173] neg_lo:[0,1] neg_hi:[0,1]
	v_pk_add_f32 v[16:17], v[12:13], v[16:17]
	v_pk_add_f32 v[10:11], v[12:13], v[10:11]
	v_pk_add_f32 v[166:167], v[14:15], v[16:17]
	v_pk_add_f32 v[12:13], v[170:171], v[10:11]
	v_rcp_f32_e32 v169, v167
	v_rcp_f32_e32 v168, v166
	v_pk_add_f32 v[14:15], v[166:167], v[14:15] neg_lo:[0,1] neg_hi:[0,1]
	v_pk_add_f32 v[170:171], v[12:13], v[170:171] neg_lo:[0,1] neg_hi:[0,1]
	v_pk_add_f32 v[14:15], v[16:17], v[14:15] neg_lo:[0,1] neg_hi:[0,1]
	v_pk_mul_f32 v[16:17], v[12:13], v[168:169]
	v_pk_add_f32 v[10:11], v[10:11], v[170:171] neg_lo:[0,1] neg_hi:[0,1]
	v_pk_mul_f32 v[170:171], v[166:167], v[16:17]
	v_cmp_neq_f32_e32 vcc, s1, v182
	v_pk_fma_f32 v[172:173], v[16:17], v[166:167], v[170:171] neg_lo:[0,0,1] neg_hi:[0,0,1]
	s_nop 0
	v_pk_fma_f32 v[172:173], v[16:17], v[14:15], v[172:173]
	s_nop 0
	v_pk_add_f32 v[174:175], v[170:171], v[172:173]
	s_nop 0
	v_pk_add_f32 v[176:177], v[12:13], v[174:175] neg_lo:[0,1] neg_hi:[0,1]
	v_pk_add_f32 v[170:171], v[174:175], v[170:171] neg_lo:[0,1] neg_hi:[0,1]
	v_pk_add_f32 v[12:13], v[12:13], v[176:177] neg_lo:[0,1] neg_hi:[0,1]
	s_nop 0
	v_pk_add_f32 v[12:13], v[12:13], v[174:175] neg_lo:[0,1] neg_hi:[0,1]
	s_nop 0
	v_pk_add_f32 v[10:11], v[10:11], v[12:13]
	v_pk_add_f32 v[12:13], v[170:171], v[172:173] neg_lo:[0,1] neg_hi:[0,1]
	s_nop 0
	v_pk_add_f32 v[10:11], v[12:13], v[10:11]
	s_nop 0
	v_pk_add_f32 v[12:13], v[176:177], v[10:11]
	s_nop 0
	v_pk_mul_f32 v[170:171], v[168:169], v[12:13]
	s_nop 0
	v_pk_mul_f32 v[172:173], v[166:167], v[170:171]
	s_nop 0
	v_pk_fma_f32 v[166:167], v[170:171], v[166:167], v[172:173] neg_lo:[0,0,1] neg_hi:[0,0,1]
	s_nop 0
	v_pk_fma_f32 v[14:15], v[170:171], v[14:15], v[166:167]
	v_pk_add_f32 v[166:167], v[176:177], v[12:13] neg_lo:[0,1] neg_hi:[0,1]
	s_nop 0
	v_pk_add_f32 v[10:11], v[10:11], v[166:167]
	v_pk_add_f32 v[166:167], v[172:173], v[14:15]
	s_nop 0
	v_pk_add_f32 v[174:175], v[12:13], v[166:167] neg_lo:[0,1] neg_hi:[0,1]
	v_pk_add_f32 v[172:173], v[166:167], v[172:173] neg_lo:[0,1] neg_hi:[0,1]
	v_pk_add_f32 v[12:13], v[12:13], v[174:175] neg_lo:[0,1] neg_hi:[0,1]
	s_nop 0
	v_pk_add_f32 v[12:13], v[12:13], v[166:167] neg_lo:[0,1] neg_hi:[0,1]
	v_cvt_f32_i32_e32 v167, v41
	v_pk_add_f32 v[10:11], v[10:11], v[12:13]
	v_pk_add_f32 v[12:13], v[172:173], v[14:15] neg_lo:[0,1] neg_hi:[0,1]
	v_cvt_f32_i32_e32 v166, v37
	v_pk_add_f32 v[10:11], v[12:13], v[10:11]
	v_pk_add_f32 v[12:13], v[16:17], v[170:171]
	v_pk_add_f32 v[10:11], v[174:175], v[10:11]
	v_pk_add_f32 v[14:15], v[12:13], v[16:17] neg_lo:[0,1] neg_hi:[0,1]
	v_pk_mul_f32 v[10:11], v[168:169], v[10:11]
; __device__ __forceinline__ float sigm(float x) { return __builtin_amdgcn_rcpf(1.0f + __expf(-x)); }
; template <int PASS>
; __device__ void lru_items(const Params& p, unsigned char* shm, int l) {
;     ...
;             { const int ch = n * 64 + (tid & 63); c0 = cw[ch]; c1 = cw[1024 + ch]; c2 = cw[2048 + ch]; c3 = cw[3072 + ch]; cb = cbias[ch]; }
; #pragma unroll
;             for (int jt = 0; jt < 4; ++jt) { const int pi = (l * 2 + (w >> 2)) * 1024 + n * 64 + jt * 16 + fr; gba[jt] = p.in[7][pi]; gbx[jt] = p.in[9][pi]; gsp[jt] = -8.0f * log1pf(__expf(-p.in[10][pi])); }
;     ...
;                   const float r = sigm(accr[i] + gba[jt]), ig = sigm(acci[i] + gbx[jt]), a = __expf(r * gsp[jt]);
	v_pk_add_f32 v[14:15], v[170:171], v[14:15] neg_lo:[0,1] neg_hi:[0,1]
	s_nop 0
	v_pk_add_f32 v[10:11], v[14:15], v[10:11]
	s_nop 0
	v_pk_add_f32 v[14:15], v[12:13], v[10:11]
	s_nop 0
	v_pk_mul_f32 v[16:17], v[14:15], v[14:15]
	v_pk_add_f32 v[12:13], v[14:15], v[12:13] neg_lo:[0,1] neg_hi:[0,1]
	v_pk_fma_f32 v[20:21], v[16:17], s[8:9], v[20:21] op_sel_hi:[1,0,0]
	v_pk_add_f32 v[10:11], v[10:11], v[12:13] neg_lo:[0,1] neg_hi:[0,1]
	v_ldexp_f32 v13, v15, 1
	v_pk_fma_f32 v[20:21], v[16:17], v[20:21], s[18:19] op_sel_hi:[1,1,0]
	v_ldexp_f32 v12, v14, 1
	v_pk_mul_f32 v[14:15], v[14:15], v[16:17]
	v_pk_mul_f32 v[16:17], v[166:167], s[28:29] op_sel_hi:[1,0]
	v_pk_mul_f32 v[14:15], v[14:15], v[20:21]
	v_pk_fma_f32 v[170:171], v[166:167], s[28:29], v[16:17] op_sel_hi:[1,0,1] neg_lo:[0,0,1] neg_hi:[0,0,1]
	v_pk_add_f32 v[20:21], v[12:13], v[14:15]
	v_ldexp_f32 v11, v11, 1
	v_pk_add_f32 v[12:13], v[20:21], v[12:13] neg_lo:[0,1] neg_hi:[0,1]
	v_pk_fma_f32 v[166:167], v[166:167], s[40:41], v[170:171] op_sel_hi:[1,0,1]
	v_pk_add_f32 v[12:13], v[14:15], v[12:13] neg_lo:[0,1] neg_hi:[0,1]
	v_ldexp_f32 v168, v10, 1
	v_mov_b32_e32 v14, v16
	v_mov_b32_e32 v15, v13
	v_mov_b32_e32 v10, v166
	v_mov_b32_e32 v169, v11
	v_pk_add_f32 v[14:15], v[14:15], v[10:11]
	v_pk_add_f32 v[10:11], v[168:169], v[12:13]
	v_mov_b32_e32 v13, v21
	v_mov_b32_e32 v169, v11
	v_pk_add_f32 v[170:171], v[16:17], v[166:167]
	v_pk_add_f32 v[12:13], v[168:169], v[12:13]
	v_pk_add_f32 v[168:169], v[20:21], v[10:11]
	v_mov_b32_e32 v176, v20
	v_pk_add_f32 v[172:173], v[170:171], v[168:169]
	v_mov_b32_e32 v174, v168
	v_mov_b32_e32 v175, v173
	v_mov_b32_e32 v177, v171
	v_pk_add_f32 v[174:175], v[174:175], v[176:177] neg_lo:[0,1] neg_hi:[0,1]
	v_mov_b32_e32 v176, v170
	v_mov_b32_e32 v177, v173
	v_mov_b32_e32 v178, v16
	v_mov_b32_e32 v179, v175
	v_pk_add_f32 v[176:177], v[176:177], v[178:179] neg_lo:[0,1] neg_hi:[0,1]
	v_mov_b32_e32 v179, v171
	v_mov_b32_e32 v180, v172
	v_mov_b32_e32 v181, v171
	v_mov_b32_e32 v171, v17
	v_mov_b32_e32 v178, v166
	v_pk_add_f32 v[16:17], v[180:181], v[170:171] neg_lo:[0,1] neg_hi:[0,1]
	v_pk_add_f32 v[178:179], v[178:179], v[176:177] neg_lo:[0,1] neg_hi:[0,1]
	v_mov_b32_e32 v177, v17
	v_pk_add_f32 v[170:171], v[166:167], v[176:177] neg_lo:[0,1] neg_hi:[0,1]
	v_pk_add_f32 v[176:177], v[168:169], v[20:21] neg_lo:[0,1] neg_hi:[0,1]
	v_pk_add_f32 v[12:13], v[12:13], v[174:175] neg_lo:[0,1] neg_hi:[0,1]
	v_mov_b32_e32 v174, v172
	v_mov_b32_e32 v175, v169
	v_mov_b32_e32 v20, v16
	v_pk_add_f32 v[20:21], v[174:175], v[20:21] neg_lo:[0,1] neg_hi:[0,1]
	v_mov_b32_e32 v169, v167
	v_pk_add_f32 v[14:15], v[14:15], v[20:21] neg_lo:[0,1] neg_hi:[0,1]
	v_pk_add_f32 v[16:17], v[168:169], v[16:17] neg_lo:[0,1] neg_hi:[0,1]
	v_pk_add_f32 v[166:167], v[12:13], v[178:179]
	v_mov_b32_e32 v179, v17
	v_mov_b32_e32 v13, v15
	v_pk_add_f32 v[20:21], v[16:17], v[14:15]
	v_pk_add_f32 v[12:13], v[178:179], v[12:13]
	v_mov_b32_e32 v14, v166
	v_pk_add_f32 v[12:13], v[12:13], v[170:171] neg_lo:[0,1] neg_hi:[0,1]
	v_mov_b32_e32 v15, v21
	v_pk_add_f32 v[10:11], v[10:11], v[176:177] neg_lo:[0,1] neg_hi:[0,1]
	v_pk_add_f32 v[14:15], v[14:15], v[12:13] neg_lo:[0,1] neg_hi:[0,1]
	v_pk_add_f32 v[10:11], v[10:11], v[12:13] neg_lo:[0,1] neg_hi:[0,1]
	v_pk_add_f32 v[14:15], v[178:179], v[14:15] neg_lo:[0,1] neg_hi:[0,1]
	v_pk_add_f32 v[12:13], v[20:21], v[166:167]
	v_pk_add_f32 v[10:11], v[10:11], v[14:15]
	v_pk_add_f32 v[14:15], v[172:173], v[12:13]
	s_nop 0
	v_pk_add_f32 v[16:17], v[14:15], v[172:173] neg_lo:[0,1] neg_hi:[0,1]
	s_nop 0
	v_pk_add_f32 v[12:13], v[12:13], v[16:17] neg_lo:[0,1] neg_hi:[0,1]
	s_nop 0
	v_pk_add_f32 v[10:11], v[10:11], v[12:13]
	s_nop 0
	v_pk_add_f32 v[10:11], v[14:15], v[10:11]
	s_nop 0
	v_cndmask_b32_e32 v10, v237, v10, vcc
	v_cmp_neq_f32_e32 vcc, s1, v0
	s_mov_b64 s[0:1], 0
	s_nop 0
	v_cndmask_b32_e32 v11, v237, v11, vcc
	v_cmp_ngt_f32_e32 vcc, -1.0, v0
	s_nop 1
	v_cndmask_b32_e32 v11, v238, v11, vcc
	v_cmp_ngt_f32_e32 vcc, -1.0, v182
	s_nop 1
	v_cndmask_b32_e32 v10, v238, v10, vcc
	v_cmp_neq_f32_e32 vcc, -1.0, v182
	s_nop 1
	v_cndmask_b32_e32 v10, v239, v10, vcc
	v_cmp_neq_f32_e32 vcc, -1.0, v0
	s_nop 1
	v_cndmask_b32_e32 v11, v239, v11, vcc
	v_cmp_lt_f32_e64 vcc, |v0|, s5
	s_nop 1
	v_cndmask_b32_e32 v11, v11, v0, vcc
	v_cmp_lt_f32_e64 vcc, |v182|, s5
	s_nop 1
	v_cndmask_b32_e32 v10, v10, v182, vcc
	v_pk_mul_f32 v[20:21], v[10:11], s[48:49] op_sel_hi:[1,0]
	s_waitcnt vmcnt(0)
	v_mul_f32_e32 v22, 0xbfb8aa3b, v22
	v_mul_f32_e32 v23, 0xbfb8aa3b, v23
	v_mul_f32_e32 v24, 0xbfb8aa3b, v24
	v_mul_f32_e32 v25, 0xbfb8aa3b, v25
	v_mul_f32_e32 v36, 0xbfb8aa3b, v36
	v_mul_f32_e32 v38, 0xbfb8aa3b, v38
	v_mul_f32_e32 v39, 0xbfb8aa3b, v39
	v_mul_f32_e32 v40, 0xbfb8aa3b, v40
	v_mul_f32_e32 v18, 0x3fb8aa3b, v18
	v_mul_f32_e32 v19, 0x3fb8aa3b, v19
	v_mul_f32_e32 v20, 0x3fb8aa3b, v20
	v_mul_f32_e32 v21, 0x3fb8aa3b, v21
